# v013 plus MLP-up accumulator clears in the epilogue, plus: in-projection also stages weight rows so a wave's halves are adjacent and stores 8 rows x 128 bytes per instruction
# speedup vs baseline: 1.0069x; 1.0065x over previous
.LBB0_174:
	s_mov_b32 s4, s0
	v_writelane_b32 v254, s4, 36
	s_mov_b64 s[12:13], s[82:83]
	v_readlane_b32 s14, v253, 32
	v_writelane_b32 v254, s5, 37
	s_mul_i32 s4, s0, 0x30000
	s_mov_b32 s5, s1
	v_writelane_b32 v254, s4, 38
	s_mov_b64 s[6:7], s[82:83]
	s_mov_b64 s[38:39], s[82:83]
	v_writelane_b32 v254, s5, 39
	s_mov_b64 s[4:5], s[82:83]
	v_mov_b32_e32 v0, v224
	v_writelane_b32 v254, s4, 40
	v_readlane_b32 s15, v253, 33
	s_and_b64 vcc, exec, s[14:15]
	v_writelane_b32 v254, s5, 41
	s_mov_b64 s[4:5], s[82:83]
	s_nop 0
	v_writelane_b32 v254, s4, 42
	s_nop 1
	v_writelane_b32 v254, s5, 43
	s_mov_b64 s[4:5], s[82:83]
	s_nop 0
	v_writelane_b32 v254, s4, 44
	s_nop 1
	v_writelane_b32 v254, s5, 45
	s_mov_b64 s[4:5], s[82:83]
	s_nop 0
	v_readfirstlane_b32 s20, v0
	s_cbranch_vccz .LBB0_208
	v_lshlrev_b32_e32 v2, 4, v0
	v_add_u32_e32 v3, 0x2000, v2
	v_ashrrev_i32_e32 v4, 31, v3
	v_lshrrev_b32_e32 v4, 22, v4
	v_add_u32_e32 v4, v3, v4
	v_ashrrev_i32_e32 v10, 10, v4
	v_mul_i32_i24_e32 v4, 0x400, v10
	v_sub_u32_e32 v3, v3, v4
	v_lshrrev_b32_e32 v4, 4, v3
	v_bitop3_b32 v3, v4, v3, 32 bitop3:0x6c
	v_ashrrev_i32_e32 v4, 31, v3
	v_lshrrev_b32_e32 v4, 26, v4
	v_readlane_b32 s14, v254, 26
	v_add_u32_e32 v4, v3, v4
	v_lshlrev_b32_e32 v5, 3, v10
	v_readlane_b32 s15, v254, 27
	v_ashrrev_i32_e32 v11, 6, v4
	v_and_b32_e32 v5, -16, v5
	s_and_b64 s[14:15], s[14:15], exec
	s_mov_b32 s0, 0x400000
	v_add_u32_e32 v5, v11, v5
	s_cselect_b32 s14, s0, 0xc00000
	s_add_u32 s0, s4, 0xc000000
	v_and_b32_e32 v6, 3, v11
	s_mov_b32 s4, 0x1fffe0
	v_lshrrev_b32_e32 v7, 2, v5
	v_lshlrev_b32_e32 v8, 1, v5
	v_and_or_b32 v6, v5, s4, v6
	v_and_b32_e32 v7, 4, v7
	v_and_b32_e32 v8, 24, v8
	v_and_b32_e32 v4, 0xc0, v4
	v_or3_b32 v6, v6, v7, v8
	v_sub_u32_e32 v3, v3, v4
	v_mov_b32_e32 v8, 1
	v_lshlrev_b32_e32 v7, 5, v10
	v_ashrrev_i16_sdwa v3, v8, sext(v3) dst_sel:DWORD dst_unused:UNUSED_PAD src0_sel:DWORD src1_sel:BYTE_0
	v_and_b32_e32 v7, 32, v7
	v_bfe_i32 v12, v3, 0, 16
	v_add_lshl_u32 v3, v7, v12, 1
	v_lshl_add_u32 v130, v6, 11, v3
	v_lshl_add_u32 v132, v5, 11, v3
	v_bfe_i32 v3, v0, 27, 1
	v_lshrrev_b32_e32 v3, 22, v3
	v_add_u32_e32 v3, v2, v3
	v_and_b32_e32 v3, 0xfffffc00, v3
	v_sub_u32_e32 v2, v2, v3
	v_lshrrev_b32_e32 v3, 4, v2
	v_ashrrev_i32_e32 v4, 31, v0
	v_bitop3_b32 v2, v3, v2, 32 bitop3:0x6c
	v_lshrrev_b32_e32 v4, 26, v4
	v_ashrrev_i32_e32 v3, 31, v2
	v_add_u32_e32 v4, v0, v4
	v_lshrrev_b32_e32 v3, 26, v3
	v_ashrrev_i32_e32 v14, 6, v4
	v_add_u32_e32 v3, v2, v3
	v_lshlrev_b32_e32 v4, 3, v14
	v_ashrrev_i32_e32 v13, 6, v3
	v_and_b32_e32 v4, -16, v4
	s_addc_u32 s17, s5, 0
	v_add_u32_e32 v4, v13, v4
	s_add_u32 s56, s6, s14
	v_and_b32_e32 v5, 3, v13
	v_lshrrev_b32_e32 v6, 2, v4
	v_lshlrev_b32_e32 v7, 1, v4
	v_and_b32_e32 v3, 0xc0, v3
	s_addc_u32 s57, s7, 0
	s_ashr_i32 s28, s20, 6
	v_and_or_b32 v5, v4, s4, v5
	v_and_b32_e32 v6, 4, v6
	v_and_b32_e32 v7, 24, v7
	v_sub_u32_e32 v2, v2, v3
	s_ashr_i32 s21, s20, 8
	s_lshl_b32 s58, s28, 10
	v_or3_b32 v5, v5, v6, v7
	v_lshlrev_b32_e32 v6, 5, v14
	v_ashrrev_i16_sdwa v2, v8, sext(v2) dst_sel:DWORD dst_unused:UNUSED_PAD src0_sel:DWORD src1_sel:BYTE_0
	v_readlane_b32 s4, v255, 61
	v_and_b32_e32 v6, 32, v6
	v_bfe_i32 v15, v2, 0, 16
	v_readlane_b32 s5, v255, 62
	s_add_u32 s4, s56, s4
	v_add_lshl_u32 v2, v6, v15, 1
	s_addc_u32 s5, s57, s5
	s_add_i32 s59, s58, 0
	v_lshl_add_u32 v134, v5, 11, v2
	v_lshrrev_b32_e32 v248, 8, v224
	v_lshl_add_u32 v134, v248, 16, v134
	v_lshl_add_u32 v130, v248, 16, v130
	v_add_u32_e32 v130, 0x20000, v130
	s_add_i32 m0, s59, 0x10000
	v_lshl_add_u32 v136, v4, 11, v2
	global_load_lds_dwordx4 v134, s[4:5]
	s_add_i32 m0, s59, 0x12000
	s_add_u32 s6, s4, 0x10000
	global_load_lds_dwordx4 v130, s[4:5]
	s_addc_u32 s7, s5, 0
	s_add_i32 m0, s59, 0x14000
	v_mov_b32_e32 v135, v1
	global_load_lds_dwordx4 v134, s[6:7]
	s_add_i32 m0, s59, 0x16000
	v_mov_b32_e32 v131, v1
	global_load_lds_dwordx4 v130, s[6:7]
	v_readlane_b32 s6, v254, 5
	v_readlane_b32 s7, v254, 6
	s_add_u32 s14, s0, s6
	s_addc_u32 s15, s17, s7
	s_add_i32 s60, s59, 0x2000
	s_mov_b32 m0, s59
	s_add_u32 s6, s14, 0x40000
	global_load_lds_dwordx4 v136, s[14:15]
	s_mov_b32 m0, s60
	s_addc_u32 s7, s15, 0
	s_add_i32 s61, s59, 0x4000
	global_load_lds_dwordx4 v132, s[14:15]
	s_mov_b32 m0, s61
	s_add_i32 s62, s59, 0x6000
	global_load_lds_dwordx4 v136, s[6:7]
	s_mov_b32 m0, s62
	v_mov_b32_e32 v137, v1
	global_load_lds_dwordx4 v132, s[6:7]
	v_mov_b32_e32 v133, v1
	s_cmp_eq_u32 s21, 1
	v_lshl_add_u64 v[8:9], s[4:5], 0, v[134:135]
	v_lshl_add_u64 v[6:7], s[4:5], 0, v[130:131]
	v_lshl_add_u64 v[2:3], s[14:15], 0, v[136:137]
	s_cselect_b64 s[6:7], -1, 0
	s_cmp_lg_u32 s21, 1
	v_lshl_add_u64 v[4:5], s[14:15], 0, v[132:133]
	s_cbranch_scc1 .LBB0_177
	s_barrier
.LBB0_177:
	v_readlane_b32 s18, v254, 38
	v_readlane_b32 s19, v254, 39
	s_lshl_b64 s[18:19], s[18:19], 2
	s_add_u32 s18, s12, s18
	s_addc_u32 s19, s13, s19
	s_cmp_eq_u64 s[12:13], 0
	s_cselect_b64 s[40:41], -1, 0
	s_cmp_lg_u64 s[12:13], 0
	s_cselect_b64 s[42:43], -1, 0
	s_add_u32 s63, s38, 0x18000000
	s_addc_u32 s64, s39, 0
	s_lshl_b32 s12, s28, 5
	s_and_b32 s28, s12, 0x60
	s_add_i32 m0, s59, 0x18000
	v_lshl_add_u64 v[8:9], v[8:9], 0, s[10:11]
	s_lshl_b32 s29, s21, 13
	s_lshl_b32 s33, s28, 7
	s_waitcnt vmcnt(2)
	s_barrier
	global_load_lds_dwordx4 v[8:9], off
	v_lshl_add_u64 v[6:7], v[6:7], 0, s[10:11]
	s_add_i32 m0, s59, 0x1a000
	s_add_i32 s65, s59, 0x8000
	s_add_i32 s66, s59, 0xa000
	global_load_lds_dwordx4 v[6:7], off
	v_lshl_add_u64 v[2:3], v[2:3], 0, s[10:11]
	s_mov_b32 m0, s65
	s_add_u32 s12, s4, 0x10080
	global_load_lds_dwordx4 v[2:3], off
	v_lshl_add_u64 v[2:3], v[4:5], 0, s[10:11]
	s_mov_b32 m0, s66
	s_addc_u32 s13, s5, 0
	global_load_lds_dwordx4 v[2:3], off
	s_add_i32 m0, s59, 0x1c000
	v_lshl_add_u64 v[2:3], s[12:13], 0, v[134:135]
	global_load_lds_dwordx4 v[2:3], off
	v_lshl_add_u64 v[2:3], s[12:13], 0, v[130:131]
	s_add_i32 m0, s59, 0x1e000
	v_readlane_b32 s12, v255, 60
	global_load_lds_dwordx4 v[2:3], off
	v_lshrrev_b32_e32 v3, 1, v0
	v_and_b32_e32 v3, 24, v3
	v_and_b32_e32 v2, 15, v0
	v_lshlrev_b32_e32 v4, 1, v3
	v_lshlrev_b32_e32 v0, 2, v0
	v_lshl_or_b32 v143, s21, 6, v2
	v_lshl_or_b32 v2, v2, 6, v4
	v_and_b32_e32 v0, 32, v0
	v_bitop3_b32 v4, v2, s29, v0 bitop3:0xde
	v_bitop3_b32 v147, v2, s33, v0 bitop3:0xde
	v_lshlrev_b32_e32 v2, 14, v10
	v_and_b32_e32 v2, 0xffff8000, v2
	v_or_b32_e32 v0, s28, v3
	v_lshl_add_u32 v2, v11, 11, v2
	v_and_b32_e32 v3, 1, v10
	v_lshl_or_b32 v2, v3, 6, v2
	v_lshl_add_u32 v138, v12, 1, v2
	v_lshlrev_b32_e32 v2, 14, v14
	v_and_b32_e32 v2, 0xffff8000, v2
	s_waitcnt vmcnt(6)
	v_lshl_add_u32 v2, v13, 11, v2
	v_and_b32_e32 v3, 1, v14
	s_cmpk_lt_u32 s20, 0x100
	v_lshl_or_b32 v2, v3, 6, v2
	s_mov_b32 s52, s12
	v_readlane_b32 s12, v254, 3
	s_cselect_b64 s[44:45], -1, 0
	v_mov_b32_e32 v139, v1
	v_lshl_add_u32 v140, v15, 1, v2
	v_mov_b32_e32 v141, v1
	s_mov_b32 s36, 0
	v_add_u32_e32 v149, 0, v4
	v_lshlrev_b32_e32 v0, 1, v0
	v_and_b32_e32 v249, 8, v228
	v_lshl_add_u32 v0, v249, 3, v0
	v_bfe_u32 v250, v224, 6, 2
	v_lshl_add_u32 v0, v250, 6, v0
	s_mov_b32 s20, s12
	s_barrier
	v_readlane_b32 s13, v254, 4
	v_lshl_add_u32 v238, s20, 8, v143
	v_mov_b32_e32 v239, 0
	v_lshl_add_u64 v[238:239], v[238:239], 2, s[18:19]
	global_load_dword v240, v[238:239], off
	global_load_dword v241, v[238:239], off offset:64
	global_load_dword v242, v[238:239], off offset:128
	global_load_dword v243, v[238:239], off offset:192
	global_load_dword v244, v[238:239], off offset:512
	global_load_dword v245, v[238:239], off offset:576
	global_load_dword v246, v[238:239], off offset:640
	global_load_dword v247, v[238:239], off offset:704
	s_mov_b32 s98, 0x00ff00ff
	s_mov_b32 s99, 0x00ff00ff
	s_mov_b32 s100, 0x1000
	s_mov_b32 s101, 0
	s_branch .LBB0_180

.LBB0_183:
	s_add_i32 s53, 0, 0x10000
	v_add_u32_e32 v142, s53, v147
	s_add_i32 s67, 0, 0x14000
	ds_read_b128 v[150:153], v142
	ds_read_b128 v[154:157], v142 offset:1024
	ds_read_b128 v[158:161], v142 offset:2048
	ds_read_b128 v[162:165], v142 offset:3072
	v_add_u32_e32 v142, s67, v147
	ds_read_b128 v[166:169], v142
	ds_read_b128 v[170:173], v142 offset:1024
	ds_read_b128 v[174:177], v142 offset:2048
	ds_read_b128 v[178:181], v142 offset:3072
	v_lshl_add_u64 v[144:145], s[4:5], 0, v[140:141]
	s_add_i32 m0, s59, 0xc000
	ds_read_b128 v[182:185], v149
	ds_read_b128 v[186:189], v149 offset:1024
	ds_read_b128 v[190:193], v149 offset:2048
	ds_read_b128 v[202:205], v149 offset:3072
	ds_read_b128 v[206:209], v149 offset:4096
	ds_read_b128 v[210:213], v149 offset:5120
	ds_read_b128 v[214:217], v149 offset:6144
	ds_read_b128 v[218:221], v149 offset:7168
	s_add_u32 s14, s4, 0xfffc0080
	s_addc_u32 s15, s5, -1
	s_cmp_eq_u32 s49, 12
	s_cselect_b32 s55, s21, s15
	s_cselect_b32 s54, s28, s14
	s_cselect_b32 s15, s29, s47
	s_cselect_b32 s14, s33, s37
	global_load_lds_dwordx4 v[144:145], off
	v_lshl_add_u64 v[144:145], s[4:5], 0, v[138:139]
	s_add_i32 m0, s59, 0xe000
	s_nop 0
	global_load_lds_dwordx4 v[144:145], off
	s_waitcnt vmcnt(8)
	s_waitcnt lgkmcnt(0)
	s_setprio 1
	s_barrier
	v_mfma_f32_16x16x32_bf16 v[126:129], v[150:153], v[182:185], v[126:129]
	v_mfma_f32_16x16x32_bf16 v[122:125], v[158:161], v[182:185], v[122:125]
	v_mfma_f32_16x16x32_bf16 v[110:113], v[150:153], v[190:193], v[110:113]
	v_mfma_f32_16x16x32_bf16 v[106:109], v[158:161], v[190:193], v[106:109]
	v_mfma_f32_16x16x32_bf16 v[94:97], v[150:153], v[206:209], v[94:97]
	v_mfma_f32_16x16x32_bf16 v[90:93], v[158:161], v[206:209], v[90:93]
	v_mfma_f32_16x16x32_bf16 v[78:81], v[150:153], v[214:217], v[78:81]
	v_mfma_f32_16x16x32_bf16 v[74:77], v[158:161], v[214:217], v[74:77]
	v_mfma_f32_16x16x32_bf16 v[126:129], v[154:157], v[186:189], v[126:129]
	v_mfma_f32_16x16x32_bf16 v[122:125], v[162:165], v[186:189], v[122:125]
	v_mfma_f32_16x16x32_bf16 v[110:113], v[154:157], v[202:205], v[110:113]
	v_mfma_f32_16x16x32_bf16 v[106:109], v[162:165], v[202:205], v[106:109]
	v_mfma_f32_16x16x32_bf16 v[94:97], v[154:157], v[210:213], v[94:97]
	v_mfma_f32_16x16x32_bf16 v[90:93], v[162:165], v[210:213], v[90:93]
	v_mfma_f32_16x16x32_bf16 v[78:81], v[154:157], v[218:221], v[78:81]
	v_mfma_f32_16x16x32_bf16 v[74:77], v[162:165], v[218:221], v[74:77]
	v_mfma_f32_16x16x32_bf16 v[118:121], v[166:169], v[182:185], v[118:121]
	v_mfma_f32_16x16x32_bf16 v[114:117], v[174:177], v[182:185], v[114:117]
	v_mfma_f32_16x16x32_bf16 v[102:105], v[166:169], v[190:193], v[102:105]
	v_mfma_f32_16x16x32_bf16 v[98:101], v[174:177], v[190:193], v[98:101]
	v_mfma_f32_16x16x32_bf16 v[86:89], v[166:169], v[206:209], v[86:89]
	v_mfma_f32_16x16x32_bf16 v[82:85], v[174:177], v[206:209], v[82:85]
	v_mfma_f32_16x16x32_bf16 v[70:73], v[166:169], v[214:217], v[70:73]
	v_mfma_f32_16x16x32_bf16 v[66:69], v[174:177], v[214:217], v[66:69]
	v_mfma_f32_16x16x32_bf16 v[118:121], v[170:173], v[186:189], v[118:121]
	v_mfma_f32_16x16x32_bf16 v[114:117], v[178:181], v[186:189], v[114:117]
	v_mfma_f32_16x16x32_bf16 v[102:105], v[170:173], v[202:205], v[102:105]
	v_mfma_f32_16x16x32_bf16 v[98:101], v[178:181], v[202:205], v[98:101]
	v_mfma_f32_16x16x32_bf16 v[86:89], v[170:173], v[210:213], v[86:89]
	v_mfma_f32_16x16x32_bf16 v[82:85], v[178:181], v[210:213], v[82:85]
	v_mfma_f32_16x16x32_bf16 v[70:73], v[170:173], v[218:221], v[70:73]
	v_mfma_f32_16x16x32_bf16 v[66:69], v[178:181], v[218:221], v[66:69]
	s_barrier
	s_setprio 0
	s_add_i32 s53, s53, s58
	v_lshl_add_u64 v[144:145], s[14:15], 0, v[134:135]
	s_mov_b32 m0, s53
	ds_read_b128 v[182:185], v149 offset:16384
	ds_read_b128 v[186:189], v149 offset:17408
	ds_read_b128 v[190:193], v149 offset:18432
	ds_read_b128 v[202:205], v149 offset:19456
	ds_read_b128 v[206:209], v149 offset:20480
	ds_read_b128 v[210:213], v149 offset:21504
	ds_read_b128 v[214:217], v149 offset:22528
	ds_read_b128 v[218:221], v149 offset:23552
	global_load_lds_dwordx4 v[144:145], off
	s_add_i32 m0, s53, 0x2000
	s_add_u32 s68, s14, 0x10000
	v_lshl_add_u64 v[222:223], s[14:15], 0, v[130:131]
	s_addc_u32 s69, s15, 0
	s_add_i32 s53, s67, s58
	global_load_lds_dwordx4 v[222:223], off
	v_lshl_add_u64 v[232:233], s[68:69], 0, v[134:135]
	s_mov_b32 m0, s53
	v_lshl_add_u64 v[234:235], s[54:55], 0, v[132:133]
	global_load_lds_dwordx4 v[232:233], off
	v_lshl_add_u64 v[232:233], s[68:69], 0, v[130:131]
	s_add_i32 m0, s53, 0x2000
	s_nop 0
	global_load_lds_dwordx4 v[232:233], off
	v_lshl_add_u64 v[232:233], s[54:55], 0, v[136:137]
	s_mov_b32 m0, s59
	s_nop 0
	global_load_lds_dwordx4 v[232:233], off
	s_mov_b32 m0, s60
	s_nop 0
	global_load_lds_dwordx4 v[234:235], off
	s_waitcnt vmcnt(8)
	s_waitcnt lgkmcnt(0)
	s_setprio 1
	s_barrier
	v_mfma_f32_16x16x32_bf16 v[62:65], v[150:153], v[182:185], v[62:65]
	v_mfma_f32_16x16x32_bf16 v[58:61], v[158:161], v[182:185], v[58:61]
	v_mfma_f32_16x16x32_bf16 v[50:53], v[150:153], v[190:193], v[50:53]
	v_mfma_f32_16x16x32_bf16 v[42:45], v[158:161], v[190:193], v[42:45]
	v_mfma_f32_16x16x32_bf16 v[34:37], v[150:153], v[206:209], v[34:37]
	v_mfma_f32_16x16x32_bf16 v[26:29], v[158:161], v[206:209], v[26:29]
	v_mfma_f32_16x16x32_bf16 v[18:21], v[150:153], v[214:217], v[18:21]
	v_mfma_f32_16x16x32_bf16 v[10:13], v[158:161], v[214:217], v[10:13]
	v_mfma_f32_16x16x32_bf16 v[62:65], v[154:157], v[186:189], v[62:65]
	v_mfma_f32_16x16x32_bf16 v[58:61], v[162:165], v[186:189], v[58:61]
	v_mfma_f32_16x16x32_bf16 v[50:53], v[154:157], v[202:205], v[50:53]
	v_mfma_f32_16x16x32_bf16 v[42:45], v[162:165], v[202:205], v[42:45]
	v_mfma_f32_16x16x32_bf16 v[34:37], v[154:157], v[210:213], v[34:37]
	v_mfma_f32_16x16x32_bf16 v[26:29], v[162:165], v[210:213], v[26:29]
	v_mfma_f32_16x16x32_bf16 v[18:21], v[154:157], v[218:221], v[18:21]
	v_mfma_f32_16x16x32_bf16 v[10:13], v[162:165], v[218:221], v[10:13]
	v_mfma_f32_16x16x32_bf16 v[54:57], v[166:169], v[182:185], v[54:57]
	v_mfma_f32_16x16x32_bf16 v[46:49], v[174:177], v[182:185], v[46:49]
	v_mfma_f32_16x16x32_bf16 v[38:41], v[166:169], v[190:193], v[38:41]
	v_mfma_f32_16x16x32_bf16 v[30:33], v[174:177], v[190:193], v[30:33]
	v_mfma_f32_16x16x32_bf16 v[22:25], v[166:169], v[206:209], v[22:25]
	v_mfma_f32_16x16x32_bf16 v[14:17], v[174:177], v[206:209], v[14:17]
	v_mfma_f32_16x16x32_bf16 v[6:9], v[166:169], v[214:217], v[6:9]
	v_mfma_f32_16x16x32_bf16 v[2:5], v[174:177], v[214:217], v[2:5]
	v_mfma_f32_16x16x32_bf16 v[54:57], v[170:173], v[186:189], v[54:57]
	v_mfma_f32_16x16x32_bf16 v[46:49], v[178:181], v[186:189], v[46:49]
	v_mfma_f32_16x16x32_bf16 v[38:41], v[170:173], v[202:205], v[38:41]
	v_mfma_f32_16x16x32_bf16 v[30:33], v[178:181], v[202:205], v[30:33]
	v_mfma_f32_16x16x32_bf16 v[22:25], v[170:173], v[210:213], v[22:25]
	v_mfma_f32_16x16x32_bf16 v[14:17], v[178:181], v[210:213], v[14:17]
	v_mfma_f32_16x16x32_bf16 v[6:9], v[170:173], v[218:221], v[6:9]
	v_mfma_f32_16x16x32_bf16 v[2:5], v[178:181], v[218:221], v[2:5]
	s_barrier
	s_setprio 0
	s_add_i32 s53, 0, 0x18000
	v_add_u32_e32 v142, s53, v147
	s_add_i32 s67, 0, 0x1c000
	ds_read_b128 v[150:153], v142
	ds_read_b128 v[154:157], v142 offset:1024
	ds_read_b128 v[158:161], v142 offset:2048
	ds_read_b128 v[162:165], v142 offset:3072
	v_add_u32_e32 v142, s67, v147
	ds_read_b128 v[166:169], v142
	ds_read_b128 v[170:173], v142 offset:1024
	ds_read_b128 v[174:177], v142 offset:2048
	ds_read_b128 v[178:181], v142 offset:3072
	s_add_u32 s54, s54, 0x40000
	s_addc_u32 s55, s55, 0
	s_mov_b32 m0, s61
	v_lshl_add_u64 v[236:237], s[54:55], 0, v[136:137]
	ds_read_b128 v[182:185], v149 offset:32768
	ds_read_b128 v[186:189], v149 offset:33792
	ds_read_b128 v[190:193], v149 offset:34816
	ds_read_b128 v[202:205], v149 offset:35840
	ds_read_b128 v[206:209], v149 offset:36864
	ds_read_b128 v[210:213], v149 offset:37888
	ds_read_b128 v[214:217], v149 offset:38912
	ds_read_b128 v[218:221], v149 offset:39936
	global_load_lds_dwordx4 v[236:237], off
	v_lshl_add_u64 v[236:237], s[54:55], 0, v[132:133]
	s_mov_b32 m0, s62
	s_nop 0
	global_load_lds_dwordx4 v[236:237], off
	s_waitcnt vmcnt(8)
	s_waitcnt lgkmcnt(0)
	s_setprio 1
	s_barrier
	v_mfma_f32_16x16x32_bf16 v[126:129], v[150:153], v[182:185], v[126:129]
	v_mfma_f32_16x16x32_bf16 v[122:125], v[158:161], v[182:185], v[122:125]
	v_mfma_f32_16x16x32_bf16 v[110:113], v[150:153], v[190:193], v[110:113]
	v_mfma_f32_16x16x32_bf16 v[106:109], v[158:161], v[190:193], v[106:109]
	v_mfma_f32_16x16x32_bf16 v[94:97], v[150:153], v[206:209], v[94:97]
	v_mfma_f32_16x16x32_bf16 v[90:93], v[158:161], v[206:209], v[90:93]
	v_mfma_f32_16x16x32_bf16 v[78:81], v[150:153], v[214:217], v[78:81]
	v_mfma_f32_16x16x32_bf16 v[74:77], v[158:161], v[214:217], v[74:77]
	v_mfma_f32_16x16x32_bf16 v[126:129], v[154:157], v[186:189], v[126:129]
	v_mfma_f32_16x16x32_bf16 v[122:125], v[162:165], v[186:189], v[122:125]
	v_mfma_f32_16x16x32_bf16 v[110:113], v[154:157], v[202:205], v[110:113]
	v_mfma_f32_16x16x32_bf16 v[106:109], v[162:165], v[202:205], v[106:109]
	v_mfma_f32_16x16x32_bf16 v[94:97], v[154:157], v[210:213], v[94:97]
	v_mfma_f32_16x16x32_bf16 v[90:93], v[162:165], v[210:213], v[90:93]
	v_mfma_f32_16x16x32_bf16 v[78:81], v[154:157], v[218:221], v[78:81]
	v_mfma_f32_16x16x32_bf16 v[74:77], v[162:165], v[218:221], v[74:77]
	v_mfma_f32_16x16x32_bf16 v[118:121], v[166:169], v[182:185], v[118:121]
	v_mfma_f32_16x16x32_bf16 v[114:117], v[174:177], v[182:185], v[114:117]
	v_mfma_f32_16x16x32_bf16 v[102:105], v[166:169], v[190:193], v[102:105]
	v_mfma_f32_16x16x32_bf16 v[98:101], v[174:177], v[190:193], v[98:101]
	v_mfma_f32_16x16x32_bf16 v[86:89], v[166:169], v[206:209], v[86:89]
	v_mfma_f32_16x16x32_bf16 v[82:85], v[174:177], v[206:209], v[82:85]
	v_mfma_f32_16x16x32_bf16 v[70:73], v[166:169], v[214:217], v[70:73]
	v_mfma_f32_16x16x32_bf16 v[66:69], v[174:177], v[214:217], v[66:69]
	v_mfma_f32_16x16x32_bf16 v[118:121], v[170:173], v[186:189], v[118:121]
	v_mfma_f32_16x16x32_bf16 v[114:117], v[178:181], v[186:189], v[114:117]
	v_mfma_f32_16x16x32_bf16 v[102:105], v[170:173], v[202:205], v[102:105]
	v_mfma_f32_16x16x32_bf16 v[98:101], v[178:181], v[202:205], v[98:101]
	v_mfma_f32_16x16x32_bf16 v[86:89], v[170:173], v[210:213], v[86:89]
	v_mfma_f32_16x16x32_bf16 v[82:85], v[178:181], v[210:213], v[82:85]
	v_mfma_f32_16x16x32_bf16 v[70:73], v[170:173], v[218:221], v[70:73]
	v_mfma_f32_16x16x32_bf16 v[66:69], v[178:181], v[218:221], v[66:69]
	s_barrier
	s_setprio 0
	s_add_i32 s53, s53, s58
	v_lshl_add_u64 v[144:145], v[144:145], 0, s[10:11]
	s_mov_b32 m0, s53
	ds_read_b128 v[182:185], v149 offset:49152
	ds_read_b128 v[186:189], v149 offset:50176
	ds_read_b128 v[190:193], v149 offset:51200
	ds_read_b128 v[202:205], v149 offset:52224
	ds_read_b128 v[206:209], v149 offset:53248
	ds_read_b128 v[210:213], v149 offset:54272
	ds_read_b128 v[214:217], v149 offset:55296
	ds_read_b128 v[218:221], v149 offset:56320
	s_add_i32 s49, s49, 2
	s_add_u32 s37, s37, 0x100
	s_addc_u32 s47, s47, 0
	s_add_u32 s4, s4, 0x100
	s_addc_u32 s5, s5, 0
	global_load_lds_dwordx4 v[144:145], off
	s_add_i32 m0, s53, 0x2000
	s_add_u32 s14, s14, 0x10080
	v_lshl_add_u64 v[144:145], v[222:223], 0, s[10:11]
	s_addc_u32 s15, s15, 0
	s_add_i32 s53, s67, s58
	global_load_lds_dwordx4 v[144:145], off
	v_lshl_add_u64 v[144:145], s[14:15], 0, v[134:135]
	s_mov_b32 m0, s53
	s_nop 0
	global_load_lds_dwordx4 v[144:145], off
	v_lshl_add_u64 v[144:145], s[14:15], 0, v[130:131]
	s_add_i32 m0, s53, 0x2000
	s_nop 0
	global_load_lds_dwordx4 v[144:145], off
	v_lshl_add_u64 v[144:145], v[232:233], 0, s[10:11]
	s_mov_b32 m0, s65
	s_nop 0
	global_load_lds_dwordx4 v[144:145], off
	v_lshl_add_u64 v[144:145], v[234:235], 0, s[10:11]
	s_mov_b32 m0, s66
	s_nop 0
	global_load_lds_dwordx4 v[144:145], off
	s_waitcnt vmcnt(8)
	s_waitcnt lgkmcnt(0)
	s_setprio 1
	s_barrier
	v_mfma_f32_16x16x32_bf16 v[62:65], v[150:153], v[182:185], v[62:65]
	v_mfma_f32_16x16x32_bf16 v[58:61], v[158:161], v[182:185], v[58:61]
	v_mfma_f32_16x16x32_bf16 v[50:53], v[150:153], v[190:193], v[50:53]
	v_mfma_f32_16x16x32_bf16 v[42:45], v[158:161], v[190:193], v[42:45]
	v_mfma_f32_16x16x32_bf16 v[34:37], v[150:153], v[206:209], v[34:37]
	v_mfma_f32_16x16x32_bf16 v[26:29], v[158:161], v[206:209], v[26:29]
	v_mfma_f32_16x16x32_bf16 v[18:21], v[150:153], v[214:217], v[18:21]
	v_mfma_f32_16x16x32_bf16 v[10:13], v[158:161], v[214:217], v[10:13]
	v_mfma_f32_16x16x32_bf16 v[62:65], v[154:157], v[186:189], v[62:65]
	v_mfma_f32_16x16x32_bf16 v[58:61], v[162:165], v[186:189], v[58:61]
	v_mfma_f32_16x16x32_bf16 v[50:53], v[154:157], v[202:205], v[50:53]
	v_mfma_f32_16x16x32_bf16 v[42:45], v[162:165], v[202:205], v[42:45]
	v_mfma_f32_16x16x32_bf16 v[34:37], v[154:157], v[210:213], v[34:37]
	v_mfma_f32_16x16x32_bf16 v[26:29], v[162:165], v[210:213], v[26:29]
	v_mfma_f32_16x16x32_bf16 v[18:21], v[154:157], v[218:221], v[18:21]
	v_mfma_f32_16x16x32_bf16 v[10:13], v[162:165], v[218:221], v[10:13]
	v_mfma_f32_16x16x32_bf16 v[54:57], v[166:169], v[182:185], v[54:57]
	v_mfma_f32_16x16x32_bf16 v[46:49], v[174:177], v[182:185], v[46:49]
	v_mfma_f32_16x16x32_bf16 v[38:41], v[166:169], v[190:193], v[38:41]
	v_mfma_f32_16x16x32_bf16 v[30:33], v[174:177], v[190:193], v[30:33]
	v_mfma_f32_16x16x32_bf16 v[22:25], v[166:169], v[206:209], v[22:25]
	v_mfma_f32_16x16x32_bf16 v[14:17], v[174:177], v[206:209], v[14:17]
	v_mfma_f32_16x16x32_bf16 v[6:9], v[166:169], v[214:217], v[6:9]
	v_mfma_f32_16x16x32_bf16 v[2:5], v[174:177], v[214:217], v[2:5]
	v_mfma_f32_16x16x32_bf16 v[54:57], v[170:173], v[186:189], v[54:57]
	v_mfma_f32_16x16x32_bf16 v[46:49], v[178:181], v[186:189], v[46:49]
	v_mfma_f32_16x16x32_bf16 v[38:41], v[170:173], v[202:205], v[38:41]
	v_mfma_f32_16x16x32_bf16 v[30:33], v[178:181], v[202:205], v[30:33]
	v_mfma_f32_16x16x32_bf16 v[22:25], v[170:173], v[210:213], v[22:25]
	v_mfma_f32_16x16x32_bf16 v[14:17], v[178:181], v[210:213], v[14:17]
	v_mfma_f32_16x16x32_bf16 v[6:9], v[170:173], v[218:221], v[6:9]
	v_mfma_f32_16x16x32_bf16 v[2:5], v[178:181], v[218:221], v[2:5]
	s_barrier
	s_setprio 0
	s_cmp_gt_u32 s49, 13
	s_cbranch_scc0 .LBB0_183
	s_and_b64 vcc, exec, s[44:45]
	s_cbranch_vccz .LBB0_186
	s_barrier
.LBB0_186:
	v_lshl_add_u32 v144, s20, 8, v143
	v_ashrrev_i32_e32 v145, 31, v144
	s_waitcnt vmcnt(8)
	v_fmamk_f32 v146, v240, 0x3a800000, v225
	v_fmamk_f32 v142, v241, 0x3a800000, v225
	v_fmamk_f32 v150, v242, 0x3a800000, v225
	v_fmamk_f32 v148, v243, 0x3a800000, v225
	v_fmamk_f32 v152, v244, 0x3a800000, v225
	v_fmamk_f32 v151, v245, 0x3a800000, v225
	v_fmamk_f32 v153, v246, 0x3a800000, v225
	v_fmamk_f32 v154, v247, 0x3a800000, v225
	s_and_b64 s[4:5], s[38:39], exec
	s_cselect_b32 s4, s48, s20
	v_lshl_add_u32 v238, s4, 8, v143
	v_mov_b32_e32 v239, 0
	v_lshl_add_u64 v[238:239], v[238:239], 2, s[18:19]
	global_load_dword v240, v[238:239], off
	global_load_dword v241, v[238:239], off offset:64
	global_load_dword v242, v[238:239], off offset:128
	global_load_dword v243, v[238:239], off offset:192
	global_load_dword v244, v[238:239], off offset:512
	global_load_dword v245, v[238:239], off offset:576
	global_load_dword v246, v[238:239], off offset:640
	global_load_dword v247, v[238:239], off offset:704
	v_and_b32_e32 v249, 8, v228
	v_sub_u32_e32 v144, v144, v249
	v_rsq_f32_e32 v142, v142
	v_rsq_f32_e32 v146, v146
	v_rsq_f32_e32 v150, v150
	s_ashr_i32 s53, s52, 31
	v_cndmask_b32_e64 v158, v142, 1.0, s[40:41]
	v_rsq_f32_e32 v142, v152
	v_rsq_f32_e32 v152, v154
	s_lshl_b64 s[4:5], s[52:53], 25
	s_add_u32 s4, s63, s4
	v_cndmask_b32_e64 v156, v146, 1.0, s[40:41]
	v_cndmask_b32_e64 v160, v150, 1.0, s[40:41]
	v_rsq_f32_e32 v146, v151
	v_rsq_f32_e32 v151, v153
	v_cndmask_b32_e64 v150, v142, 1.0, s[40:41]
	v_cndmask_b32_e64 v142, v152, 1.0, s[40:41]
	s_addc_u32 s5, s64, s5
	v_lshlrev_b64 v[152:153], 9, v[144:145]
	v_lshl_add_u64 v[152:153], s[4:5], 0, v[152:153]
	v_lshl_add_u64 v[152:153], v[152:153], 0, v[0:1]
	v_pk_mul_f32 v[128:129], v[128:129], v[156:157] op_sel_hi:[1,0]
	v_pk_mul_f32 v[126:127], v[126:127], v[156:157] op_sel_hi:[1,0]
	v_pk_mul_f32 v[154:155], v[124:125], v[156:157] op_sel_hi:[1,0]
	v_pk_mul_f32 v[124:125], v[122:123], v[156:157] op_sel_hi:[1,0]
	v_cvt_pk_bf16_f32 v122, v126, v127
	v_cvt_pk_bf16_f32 v123, v128, v129
	v_pk_mul_f32 v[118:119], v[118:119], v[156:157] op_sel_hi:[1,0]
	v_cvt_pk_bf16_f32 v124, v124, v125
	v_cvt_pk_bf16_f32 v125, v154, v155
	v_mov_b32_e32 v248, v122
	v_mov_b32_e32 v249, v123
	v_mov_b32_e32 v250, v124
	v_mov_b32_e32 v251, v125
	v_pk_mul_f32 v[120:121], v[120:121], v[156:157] op_sel_hi:[1,0]
	v_pk_mul_f32 v[112:113], v[112:113], v[158:159] op_sel_hi:[1,0]
	v_pk_mul_f32 v[122:123], v[116:117], v[156:157] op_sel_hi:[1,0]
	v_pk_mul_f32 v[116:117], v[114:115], v[156:157] op_sel_hi:[1,0]
	v_cvt_pk_bf16_f32 v114, v118, v119
	v_cvt_pk_bf16_f32 v115, v120, v121
	v_pk_mul_f32 v[110:111], v[110:111], v[158:159] op_sel_hi:[1,0]
	v_cvt_pk_bf16_f32 v116, v116, v117
	v_cvt_pk_bf16_f32 v117, v122, v123
	v_mov_b32_dpp v252, v248 row_ror:8 row_mask:0xf bank_mask:0xf
	v_mov_b32_dpp v226, v114 row_ror:8 row_mask:0xf bank_mask:0xf
	v_cndmask_b32_e64 v114, v114, v252, s[98:99]
	v_cndmask_b32_e64 v248, v226, v248, s[98:99]
	v_mov_b32_dpp v252, v249 row_ror:8 row_mask:0xf bank_mask:0xf
	v_mov_b32_dpp v226, v115 row_ror:8 row_mask:0xf bank_mask:0xf
	v_cndmask_b32_e64 v115, v115, v252, s[98:99]
	v_cndmask_b32_e64 v249, v226, v249, s[98:99]
	v_mov_b32_dpp v252, v250 row_ror:8 row_mask:0xf bank_mask:0xf
	v_mov_b32_dpp v226, v116 row_ror:8 row_mask:0xf bank_mask:0xf
	v_cndmask_b32_e64 v116, v116, v252, s[98:99]
	v_cndmask_b32_e64 v250, v226, v250, s[98:99]
	v_mov_b32_dpp v252, v251 row_ror:8 row_mask:0xf bank_mask:0xf
	v_mov_b32_dpp v226, v117 row_ror:8 row_mask:0xf bank_mask:0xf
	v_cndmask_b32_e64 v117, v117, v252, s[98:99]
	v_cndmask_b32_e64 v251, v226, v251, s[98:99]
	v_lshl_add_u64 v[226:227], v[152:153], 0, s[100:101]
	flat_store_dwordx4 v[152:153], v[248:251]
	flat_store_dwordx4 v[226:227], v[114:117]
	v_pk_mul_f32 v[102:103], v[102:103], v[158:159] op_sel_hi:[1,0]
	v_pk_mul_f32 v[104:105], v[104:105], v[158:159] op_sel_hi:[1,0]
	v_or_b32_e32 v114, 16, v144
	v_ashrrev_i32_e32 v115, 31, v114
	v_lshlrev_b64 v[114:115], 9, v[114:115]
	v_lshl_add_u64 v[114:115], s[4:5], 0, v[114:115]
	v_lshl_add_u64 v[114:115], v[114:115], 0, v[0:1]
	v_pk_mul_f32 v[116:117], v[108:109], v[158:159] op_sel_hi:[1,0]
	v_pk_mul_f32 v[108:109], v[106:107], v[158:159] op_sel_hi:[1,0]
	v_cvt_pk_bf16_f32 v106, v110, v111
	v_cvt_pk_bf16_f32 v107, v112, v113
	v_pk_mul_f32 v[96:97], v[96:97], v[160:161] op_sel_hi:[1,0]
	v_cvt_pk_bf16_f32 v108, v108, v109
	v_cvt_pk_bf16_f32 v109, v116, v117
	v_mov_b32_e32 v248, v106
	v_mov_b32_e32 v249, v107
	v_mov_b32_e32 v250, v108
	v_mov_b32_e32 v251, v109
	v_pk_mul_f32 v[94:95], v[94:95], v[160:161] op_sel_hi:[1,0]
	v_rsq_f32_e32 v148, v148
	v_pk_mul_f32 v[106:107], v[100:101], v[158:159] op_sel_hi:[1,0]
	v_pk_mul_f32 v[100:101], v[98:99], v[158:159] op_sel_hi:[1,0]
	v_cvt_pk_bf16_f32 v98, v102, v103
	v_cvt_pk_bf16_f32 v99, v104, v105
	v_pk_mul_f32 v[86:87], v[86:87], v[160:161] op_sel_hi:[1,0]
	v_cvt_pk_bf16_f32 v100, v100, v101
	v_cvt_pk_bf16_f32 v101, v106, v107
	v_mov_b32_dpp v252, v248 row_ror:8 row_mask:0xf bank_mask:0xf
	v_mov_b32_dpp v226, v98 row_ror:8 row_mask:0xf bank_mask:0xf
	v_cndmask_b32_e64 v98, v98, v252, s[98:99]
	v_cndmask_b32_e64 v248, v226, v248, s[98:99]
	v_mov_b32_dpp v252, v249 row_ror:8 row_mask:0xf bank_mask:0xf
	v_mov_b32_dpp v226, v99 row_ror:8 row_mask:0xf bank_mask:0xf
	v_cndmask_b32_e64 v99, v99, v252, s[98:99]
	v_cndmask_b32_e64 v249, v226, v249, s[98:99]
	v_mov_b32_dpp v252, v250 row_ror:8 row_mask:0xf bank_mask:0xf
	v_mov_b32_dpp v226, v100 row_ror:8 row_mask:0xf bank_mask:0xf
	v_cndmask_b32_e64 v100, v100, v252, s[98:99]
	v_cndmask_b32_e64 v250, v226, v250, s[98:99]
	v_mov_b32_dpp v252, v251 row_ror:8 row_mask:0xf bank_mask:0xf
	v_mov_b32_dpp v226, v101 row_ror:8 row_mask:0xf bank_mask:0xf
	v_cndmask_b32_e64 v101, v101, v252, s[98:99]
	v_cndmask_b32_e64 v251, v226, v251, s[98:99]
	v_lshl_add_u64 v[226:227], v[114:115], 0, s[100:101]
	flat_store_dwordx4 v[114:115], v[248:251]
	flat_store_dwordx4 v[226:227], v[98:101]
	v_pk_mul_f32 v[88:89], v[88:89], v[160:161] op_sel_hi:[1,0]
	v_cndmask_b32_e64 v162, v148, 1.0, s[40:41]
	v_or_b32_e32 v98, 32, v144
	v_ashrrev_i32_e32 v99, 31, v98
	v_lshlrev_b64 v[98:99], 9, v[98:99]
	v_lshl_add_u64 v[98:99], s[4:5], 0, v[98:99]
	v_lshl_add_u64 v[98:99], v[98:99], 0, v[0:1]
	v_pk_mul_f32 v[100:101], v[92:93], v[160:161] op_sel_hi:[1,0]
	v_pk_mul_f32 v[92:93], v[90:91], v[160:161] op_sel_hi:[1,0]
	v_cvt_pk_bf16_f32 v90, v94, v95
	v_cvt_pk_bf16_f32 v91, v96, v97
	v_pk_mul_f32 v[80:81], v[80:81], v[162:163] op_sel_hi:[1,0]
	v_cvt_pk_bf16_f32 v92, v92, v93
	v_cvt_pk_bf16_f32 v93, v100, v101
	v_mov_b32_e32 v248, v90
	v_mov_b32_e32 v249, v91
	v_mov_b32_e32 v250, v92
	v_mov_b32_e32 v251, v93
	v_pk_mul_f32 v[78:79], v[78:79], v[162:163] op_sel_hi:[1,0]
	v_pk_mul_f32 v[72:73], v[72:73], v[162:163] op_sel_hi:[1,0]
	v_pk_mul_f32 v[90:91], v[84:85], v[160:161] op_sel_hi:[1,0]
	v_pk_mul_f32 v[84:85], v[82:83], v[160:161] op_sel_hi:[1,0]
	v_cvt_pk_bf16_f32 v82, v86, v87
	v_cvt_pk_bf16_f32 v83, v88, v89
	v_pk_mul_f32 v[70:71], v[70:71], v[162:163] op_sel_hi:[1,0]
	v_cvt_pk_bf16_f32 v84, v84, v85
	v_cvt_pk_bf16_f32 v85, v90, v91
	v_mov_b32_dpp v252, v248 row_ror:8 row_mask:0xf bank_mask:0xf
	v_mov_b32_dpp v226, v82 row_ror:8 row_mask:0xf bank_mask:0xf
	v_cndmask_b32_e64 v82, v82, v252, s[98:99]
	v_cndmask_b32_e64 v248, v226, v248, s[98:99]
	v_mov_b32_dpp v252, v249 row_ror:8 row_mask:0xf bank_mask:0xf
	v_mov_b32_dpp v226, v83 row_ror:8 row_mask:0xf bank_mask:0xf
	v_cndmask_b32_e64 v83, v83, v252, s[98:99]
	v_cndmask_b32_e64 v249, v226, v249, s[98:99]
	v_mov_b32_dpp v252, v250 row_ror:8 row_mask:0xf bank_mask:0xf
	v_mov_b32_dpp v226, v84 row_ror:8 row_mask:0xf bank_mask:0xf
	v_cndmask_b32_e64 v84, v84, v252, s[98:99]
	v_cndmask_b32_e64 v250, v226, v250, s[98:99]
	v_mov_b32_dpp v252, v251 row_ror:8 row_mask:0xf bank_mask:0xf
	v_mov_b32_dpp v226, v85 row_ror:8 row_mask:0xf bank_mask:0xf
	v_cndmask_b32_e64 v85, v85, v252, s[98:99]
	v_cndmask_b32_e64 v251, v226, v251, s[98:99]
	v_lshl_add_u64 v[226:227], v[98:99], 0, s[100:101]
	flat_store_dwordx4 v[98:99], v[248:251]
	flat_store_dwordx4 v[226:227], v[82:85]
	v_pk_mul_f32 v[62:63], v[62:63], v[150:151] op_sel_hi:[1,0]
	v_pk_mul_f32 v[64:65], v[64:65], v[150:151] op_sel_hi:[1,0]
	v_or_b32_e32 v82, 48, v144
	v_ashrrev_i32_e32 v83, 31, v82
	v_lshlrev_b64 v[82:83], 9, v[82:83]
	v_lshl_add_u64 v[82:83], s[4:5], 0, v[82:83]
	v_lshl_add_u64 v[82:83], v[82:83], 0, v[0:1]
	v_pk_mul_f32 v[84:85], v[76:77], v[162:163] op_sel_hi:[1,0]
	v_pk_mul_f32 v[76:77], v[74:75], v[162:163] op_sel_hi:[1,0]
	v_cvt_pk_bf16_f32 v74, v78, v79
	v_cvt_pk_bf16_f32 v75, v80, v81
	v_cndmask_b32_e64 v148, v146, 1.0, s[40:41]
	v_cvt_pk_bf16_f32 v76, v76, v77
	v_cvt_pk_bf16_f32 v77, v84, v85
	v_mov_b32_e32 v248, v74
	v_mov_b32_e32 v249, v75
	v_mov_b32_e32 v250, v76
	v_mov_b32_e32 v251, v77
	v_pk_mul_f32 v[56:57], v[56:57], v[150:151] op_sel_hi:[1,0]
	v_pk_mul_f32 v[54:55], v[54:55], v[150:151] op_sel_hi:[1,0]
	v_pk_mul_f32 v[74:75], v[68:69], v[162:163] op_sel_hi:[1,0]
	v_pk_mul_f32 v[68:69], v[66:67], v[162:163] op_sel_hi:[1,0]
	v_cvt_pk_bf16_f32 v66, v70, v71
	v_cvt_pk_bf16_f32 v67, v72, v73
	v_pk_mul_f32 v[70:71], v[60:61], v[150:151] op_sel_hi:[1,0]
	v_cvt_pk_bf16_f32 v68, v68, v69
	v_cvt_pk_bf16_f32 v69, v74, v75
	v_mov_b32_dpp v252, v248 row_ror:8 row_mask:0xf bank_mask:0xf
	v_mov_b32_dpp v226, v66 row_ror:8 row_mask:0xf bank_mask:0xf
	v_cndmask_b32_e64 v66, v66, v252, s[98:99]
	v_cndmask_b32_e64 v248, v226, v248, s[98:99]
	v_mov_b32_dpp v252, v249 row_ror:8 row_mask:0xf bank_mask:0xf
	v_mov_b32_dpp v226, v67 row_ror:8 row_mask:0xf bank_mask:0xf
	v_cndmask_b32_e64 v67, v67, v252, s[98:99]
	v_cndmask_b32_e64 v249, v226, v249, s[98:99]
	v_mov_b32_dpp v252, v250 row_ror:8 row_mask:0xf bank_mask:0xf
	v_mov_b32_dpp v226, v68 row_ror:8 row_mask:0xf bank_mask:0xf
	v_cndmask_b32_e64 v68, v68, v252, s[98:99]
	v_cndmask_b32_e64 v250, v226, v250, s[98:99]
	v_mov_b32_dpp v252, v251 row_ror:8 row_mask:0xf bank_mask:0xf
	v_mov_b32_dpp v226, v69 row_ror:8 row_mask:0xf bank_mask:0xf
	v_cndmask_b32_e64 v69, v69, v252, s[98:99]
	v_cndmask_b32_e64 v251, v226, v251, s[98:99]
	v_lshl_add_u64 v[226:227], v[82:83], 0, s[100:101]
	flat_store_dwordx4 v[82:83], v[248:251]
	flat_store_dwordx4 v[226:227], v[66:69]
	v_pk_mul_f32 v[60:61], v[58:59], v[150:151] op_sel_hi:[1,0]
	v_cvt_pk_bf16_f32 v58, v62, v63
	v_cvt_pk_bf16_f32 v59, v64, v65
	v_pk_mul_f32 v[50:51], v[50:51], v[148:149] op_sel_hi:[1,0]
	v_lshlrev_b64 v[66:67], 9, v[144:145]
	v_lshl_add_u64 v[66:67], s[4:5], 0, v[66:67]
	v_lshl_add_u64 v[66:67], v[66:67], 0, v[0:1]
	s_mov_b32 s4, 0x10000
	v_add_co_u32_e32 v62, vcc, s4, v66
	v_cvt_pk_bf16_f32 v60, v60, v61
	v_cvt_pk_bf16_f32 v61, v70, v71
	v_lshl_add_u64 v[68:69], v[66:67], 0, s[84:85]
	s_nop 0
	v_addc_co_u32_e32 v63, vcc, 0, v67, vcc
	v_mov_b32_e32 v248, v58
	v_mov_b32_e32 v249, v59
	v_mov_b32_e32 v250, v60
	v_mov_b32_e32 v251, v61
	s_mov_b64 s[4:5], 0x12000
	v_cndmask_b32_e64 v146, v151, 1.0, s[40:41]
	v_pk_mul_f32 v[58:59], v[48:49], v[150:151] op_sel_hi:[1,0]
	v_pk_mul_f32 v[48:49], v[46:47], v[150:151] op_sel_hi:[1,0]
	v_cvt_pk_bf16_f32 v46, v54, v55
	v_cvt_pk_bf16_f32 v47, v56, v57
	v_pk_mul_f32 v[40:41], v[40:41], v[148:149] op_sel_hi:[1,0]
	v_cvt_pk_bf16_f32 v48, v48, v49
	v_cvt_pk_bf16_f32 v49, v58, v59
	v_mov_b32_dpp v252, v248 row_ror:8 row_mask:0xf bank_mask:0xf
	v_mov_b32_dpp v226, v46 row_ror:8 row_mask:0xf bank_mask:0xf
	v_cndmask_b32_e64 v46, v46, v252, s[98:99]
	v_cndmask_b32_e64 v248, v226, v248, s[98:99]
	v_mov_b32_dpp v252, v249 row_ror:8 row_mask:0xf bank_mask:0xf
	v_mov_b32_dpp v226, v47 row_ror:8 row_mask:0xf bank_mask:0xf
	v_cndmask_b32_e64 v47, v47, v252, s[98:99]
	v_cndmask_b32_e64 v249, v226, v249, s[98:99]
	v_mov_b32_dpp v252, v250 row_ror:8 row_mask:0xf bank_mask:0xf
	v_mov_b32_dpp v226, v48 row_ror:8 row_mask:0xf bank_mask:0xf
	v_cndmask_b32_e64 v48, v48, v252, s[98:99]
	v_cndmask_b32_e64 v250, v226, v250, s[98:99]
	v_mov_b32_dpp v252, v251 row_ror:8 row_mask:0xf bank_mask:0xf
	v_mov_b32_dpp v226, v49 row_ror:8 row_mask:0xf bank_mask:0xf
	v_cndmask_b32_e64 v49, v49, v252, s[98:99]
	v_cndmask_b32_e64 v251, v226, v251, s[98:99]
	v_lshl_add_u64 v[226:227], v[68:69], 0, s[100:101]
	flat_store_dwordx4 v[68:69], v[248:251]
	flat_store_dwordx4 v[226:227], v[46:49]
	v_pk_mul_f32 v[38:39], v[38:39], v[148:149] op_sel_hi:[1,0]
	v_pk_mul_f32 v[34:35], v[34:35], v[146:147] op_sel_hi:[1,0]
	v_lshl_add_u64 v[46:47], v[66:67], 0, s[4:5]
	v_pk_mul_f32 v[48:49], v[52:53], v[148:149] op_sel_hi:[1,0]
	s_mov_b32 s4, 0x12000
	v_pk_mul_f32 v[52:53], v[44:45], v[148:149] op_sel_hi:[1,0]
	v_pk_mul_f32 v[44:45], v[42:43], v[148:149] op_sel_hi:[1,0]
	v_cvt_pk_bf16_f32 v42, v50, v51
	v_cvt_pk_bf16_f32 v43, v48, v49
	v_add_co_u32_e32 v48, vcc, s4, v66
	v_cvt_pk_bf16_f32 v44, v44, v45
	v_cvt_pk_bf16_f32 v45, v52, v53
	s_mov_b64 s[4:5], 0x14000
	s_nop 0
	v_addc_co_u32_e32 v49, vcc, 0, v67, vcc
	v_mov_b32_e32 v248, v42
	v_mov_b32_e32 v249, v43
	v_mov_b32_e32 v250, v44
	v_mov_b32_e32 v251, v45
	v_pk_mul_f32 v[24:25], v[24:25], v[146:147] op_sel_hi:[1,0]
	v_pk_mul_f32 v[22:23], v[22:23], v[146:147] op_sel_hi:[1,0]
	v_pk_mul_f32 v[42:43], v[32:33], v[148:149] op_sel_hi:[1,0]
	v_pk_mul_f32 v[32:33], v[30:31], v[148:149] op_sel_hi:[1,0]
	v_cvt_pk_bf16_f32 v30, v38, v39
	v_cvt_pk_bf16_f32 v31, v40, v41
	v_pk_mul_f32 v[18:19], v[18:19], v[142:143] op_sel_hi:[1,0]
	v_cvt_pk_bf16_f32 v32, v32, v33
	v_cvt_pk_bf16_f32 v33, v42, v43
	v_mov_b32_dpp v252, v248 row_ror:8 row_mask:0xf bank_mask:0xf
	v_mov_b32_dpp v226, v30 row_ror:8 row_mask:0xf bank_mask:0xf
	v_cndmask_b32_e64 v30, v30, v252, s[98:99]
	v_cndmask_b32_e64 v248, v226, v248, s[98:99]
	v_mov_b32_dpp v252, v249 row_ror:8 row_mask:0xf bank_mask:0xf
	v_mov_b32_dpp v226, v31 row_ror:8 row_mask:0xf bank_mask:0xf
	v_cndmask_b32_e64 v31, v31, v252, s[98:99]
	v_cndmask_b32_e64 v249, v226, v249, s[98:99]
	v_mov_b32_dpp v252, v250 row_ror:8 row_mask:0xf bank_mask:0xf
	v_mov_b32_dpp v226, v32 row_ror:8 row_mask:0xf bank_mask:0xf
	v_cndmask_b32_e64 v32, v32, v252, s[98:99]
	v_cndmask_b32_e64 v250, v226, v250, s[98:99]
	v_mov_b32_dpp v252, v251 row_ror:8 row_mask:0xf bank_mask:0xf
	v_mov_b32_dpp v226, v33 row_ror:8 row_mask:0xf bank_mask:0xf
	v_cndmask_b32_e64 v33, v33, v252, s[98:99]
	v_cndmask_b32_e64 v251, v226, v251, s[98:99]
	v_lshl_add_u64 v[226:227], v[46:47], 0, s[100:101]
	flat_store_dwordx4 v[46:47], v[248:251]
	flat_store_dwordx4 v[226:227], v[30:33]
	v_pk_mul_f32 v[8:9], v[8:9], v[142:143] op_sel_hi:[1,0]
	v_pk_mul_f32 v[6:7], v[6:7], v[142:143] op_sel_hi:[1,0]
	v_lshl_add_u64 v[30:31], v[66:67], 0, s[4:5]
	v_pk_mul_f32 v[32:33], v[36:37], v[146:147] op_sel_hi:[1,0]
	s_mov_b32 s4, 0x14000
	v_pk_mul_f32 v[36:37], v[28:29], v[146:147] op_sel_hi:[1,0]
	v_pk_mul_f32 v[28:29], v[26:27], v[146:147] op_sel_hi:[1,0]
	v_cvt_pk_bf16_f32 v26, v34, v35
	v_cvt_pk_bf16_f32 v27, v32, v33
	v_add_co_u32_e32 v32, vcc, s4, v66
	v_cvt_pk_bf16_f32 v28, v28, v29
	v_cvt_pk_bf16_f32 v29, v36, v37
	s_mov_b64 s[4:5], 0x16000
	s_nop 0
	v_addc_co_u32_e32 v33, vcc, 0, v67, vcc
	v_mov_b32_e32 v248, v26
	v_mov_b32_e32 v249, v27
	v_mov_b32_e32 v250, v28
	v_mov_b32_e32 v251, v29
	s_nop 1
	v_pk_mul_f32 v[26:27], v[16:17], v[146:147] op_sel_hi:[1,0]
	v_pk_mul_f32 v[16:17], v[14:15], v[146:147] op_sel_hi:[1,0]
	v_cvt_pk_bf16_f32 v14, v22, v23
	v_cvt_pk_bf16_f32 v15, v24, v25
	s_nop 0
	v_cvt_pk_bf16_f32 v16, v16, v17
	v_cvt_pk_bf16_f32 v17, v26, v27
	v_mov_b32_dpp v252, v248 row_ror:8 row_mask:0xf bank_mask:0xf
	v_mov_b32_dpp v226, v14 row_ror:8 row_mask:0xf bank_mask:0xf
	v_cndmask_b32_e64 v14, v14, v252, s[98:99]
	v_cndmask_b32_e64 v248, v226, v248, s[98:99]
	v_mov_b32_dpp v252, v249 row_ror:8 row_mask:0xf bank_mask:0xf
	v_mov_b32_dpp v226, v15 row_ror:8 row_mask:0xf bank_mask:0xf
	v_cndmask_b32_e64 v15, v15, v252, s[98:99]
	v_cndmask_b32_e64 v249, v226, v249, s[98:99]
	v_mov_b32_dpp v252, v250 row_ror:8 row_mask:0xf bank_mask:0xf
	v_mov_b32_dpp v226, v16 row_ror:8 row_mask:0xf bank_mask:0xf
	v_cndmask_b32_e64 v16, v16, v252, s[98:99]
	v_cndmask_b32_e64 v250, v226, v250, s[98:99]
	v_mov_b32_dpp v252, v251 row_ror:8 row_mask:0xf bank_mask:0xf
	v_mov_b32_dpp v226, v17 row_ror:8 row_mask:0xf bank_mask:0xf
	v_cndmask_b32_e64 v17, v17, v252, s[98:99]
	v_cndmask_b32_e64 v251, v226, v251, s[98:99]
	v_lshl_add_u64 v[226:227], v[30:31], 0, s[100:101]
	flat_store_dwordx4 v[30:31], v[248:251]
	flat_store_dwordx4 v[226:227], v[14:17]
	s_nop 1
	v_lshl_add_u64 v[14:15], v[66:67], 0, s[4:5]
	v_pk_mul_f32 v[16:17], v[20:21], v[142:143] op_sel_hi:[1,0]
	s_mov_b32 s4, 0x16000
	v_pk_mul_f32 v[20:21], v[12:13], v[142:143] op_sel_hi:[1,0]
	v_pk_mul_f32 v[12:13], v[10:11], v[142:143] op_sel_hi:[1,0]
	v_cvt_pk_bf16_f32 v10, v18, v19
	v_cvt_pk_bf16_f32 v11, v16, v17
	v_add_co_u32_e32 v16, vcc, s4, v66
	v_cvt_pk_bf16_f32 v12, v12, v13
	v_cvt_pk_bf16_f32 v13, v20, v21
	s_mov_b64 s[4:5], -1
	s_nop 0
	v_addc_co_u32_e32 v17, vcc, 0, v67, vcc
	v_mov_b32_e32 v248, v10
	v_mov_b32_e32 v249, v11
	v_mov_b32_e32 v250, v12
	v_mov_b32_e32 v251, v13
	s_andn2_b64 vcc, exec, s[38:39]
	s_nop 0
	v_pk_mul_f32 v[10:11], v[4:5], v[142:143] op_sel_hi:[1,0]
	v_pk_mul_f32 v[4:5], v[2:3], v[142:143] op_sel_hi:[1,0]
	v_cvt_pk_bf16_f32 v2, v6, v7
	v_cvt_pk_bf16_f32 v3, v8, v9
	s_nop 0
	v_cvt_pk_bf16_f32 v4, v4, v5
	v_cvt_pk_bf16_f32 v5, v10, v11
	v_mov_b32_dpp v252, v248 row_ror:8 row_mask:0xf bank_mask:0xf
	v_mov_b32_dpp v226, v2 row_ror:8 row_mask:0xf bank_mask:0xf
	v_cndmask_b32_e64 v2, v2, v252, s[98:99]
	v_cndmask_b32_e64 v248, v226, v248, s[98:99]
	v_mov_b32_dpp v252, v249 row_ror:8 row_mask:0xf bank_mask:0xf
	v_mov_b32_dpp v226, v3 row_ror:8 row_mask:0xf bank_mask:0xf
	v_cndmask_b32_e64 v3, v3, v252, s[98:99]
	v_cndmask_b32_e64 v249, v226, v249, s[98:99]
	v_mov_b32_dpp v252, v250 row_ror:8 row_mask:0xf bank_mask:0xf
	v_mov_b32_dpp v226, v4 row_ror:8 row_mask:0xf bank_mask:0xf
	v_cndmask_b32_e64 v4, v4, v252, s[98:99]
	v_cndmask_b32_e64 v250, v226, v250, s[98:99]
	v_mov_b32_dpp v252, v251 row_ror:8 row_mask:0xf bank_mask:0xf
	v_mov_b32_dpp v226, v5 row_ror:8 row_mask:0xf bank_mask:0xf
	v_cndmask_b32_e64 v5, v5, v252, s[98:99]
	v_cndmask_b32_e64 v251, v226, v251, s[98:99]
	v_lshl_add_u64 v[226:227], v[14:15], 0, s[100:101]
	flat_store_dwordx4 v[14:15], v[248:251]
	flat_store_dwordx4 v[226:227], v[2:5]
	s_cbranch_vccnz .LBB0_179
	s_andn2_b64 vcc, exec, s[6:7]
	s_cbranch_vccnz .LBB0_178
	s_barrier
	s_branch .LBB0_178

.LBB0_551:
	v_lshrrev_b32_e32 v18, 1, v16
	s_add_u32 s42, s40, 0x18000000
	v_and_b32_e32 v18, 24, v18
	s_addc_u32 s43, s41, 0
	v_and_b32_e32 v17, 15, v16
	v_lshlrev_b32_e32 v19, 1, v18
	v_lshlrev_b32_e32 v16, 2, v16
	s_lshl_b32 s21, s21, 5
	v_lshl_or_b32 v141, s28, 6, v17
	v_lshl_or_b32 v17, v17, 6, v19
	s_lshl_b32 s28, s28, 13
	v_and_b32_e32 v16, 32, v16
	s_and_b32 s21, s21, 0x60
	s_add_i32 m0, s59, 0x18000
	v_lshl_add_u64 v[8:9], v[8:9], 0, s[10:11]
	v_bitop3_b32 v19, v17, s28, v16 bitop3:0xde
	s_lshl_b32 s28, s21, 7
	s_waitcnt vmcnt(2)
	s_barrier
	global_load_lds_dwordx4 v[8:9], off
	v_lshl_add_u64 v[6:7], v[6:7], 0, s[10:11]
	s_add_i32 m0, s59, 0x1a000
	s_add_i32 s63, s59, 0x8000
	s_add_i32 s64, s59, 0xa000
	v_bitop3_b32 v145, v17, s28, v16 bitop3:0xde
	global_load_lds_dwordx4 v[6:7], off
	v_lshl_add_u64 v[2:3], v[2:3], 0, s[10:11]
	s_mov_b32 m0, s63
	s_add_u32 s28, s12, 0x10080
	global_load_lds_dwordx4 v[2:3], off
	v_lshl_add_u64 v[2:3], v[4:5], 0, s[10:11]
	s_mov_b32 m0, s64
	s_addc_u32 s29, s13, 0
	global_load_lds_dwordx4 v[2:3], off
	s_add_i32 m0, s59, 0x1c000
	v_lshl_add_u64 v[2:3], s[28:29], 0, v[0:1]
	global_load_lds_dwordx4 v[2:3], off
	v_lshl_add_u64 v[2:3], s[28:29], 0, v[130:131]
	s_add_i32 m0, s59, 0x1e000
	s_cmpk_lt_u32 s20, 0x100
	global_load_lds_dwordx4 v[2:3], off
	v_lshlrev_b32_e32 v2, 14, v10
	v_and_b32_e32 v2, 0xffff8000, v2
	v_lshl_add_u32 v2, v11, 11, v2
	v_and_b32_e32 v3, 1, v10
	v_lshl_or_b32 v2, v3, 6, v2
	v_lshl_add_u32 v136, v12, 1, v2
	v_lshlrev_b32_e32 v2, 14, v14
	v_and_b32_e32 v2, 0xffff8000, v2
	s_waitcnt vmcnt(6)
	v_lshl_add_u32 v2, v13, 11, v2
	v_and_b32_e32 v3, 1, v14
	v_lshl_or_b32 v2, v3, 6, v2
	v_readlane_b32 s26, v255, 63
	s_cselect_b64 s[44:45], -1, 0
	s_waitcnt vmcnt(0)
	v_or_b32_e32 v147, s21, v18
	v_mov_b32_e32 v137, v1
	v_lshl_add_u32 v138, v15, 1, v2
	v_mov_b32_e32 v139, v1
	s_mov_b32 s65, 0
	v_add_u32_e32 v149, 0, v19
	v_readlane_b32 s20, v255, 56
	s_mov_b32 s21, s26
	s_barrier
	v_readlane_b32 s27, v254, 0
	v_lshl_add_u32 v238, s21, 8, v141
	v_mov_b32_e32 v239, 0
	v_lshl_add_u64 v[238:239], v[238:239], 2, s[4:5]
	global_load_dword v240, v[238:239], off
	global_load_dword v241, v[238:239], off offset:64
	global_load_dword v242, v[238:239], off offset:128
	global_load_dword v243, v[238:239], off offset:192
	global_load_dword v244, v[238:239], off offset:512
	global_load_dword v245, v[238:239], off offset:576
	global_load_dword v246, v[238:239], off offset:640
	global_load_dword v247, v[238:239], off offset:704
	s_mov_b32 s98, 0x00ff00ff
	s_mov_b32 s99, 0x00ff00ff
	s_mov_b32 s100, 0x10000
	s_mov_b32 s101, 0
	v_mov_b32_e32 v6, 0
	v_mov_b32_e32 v7, 0
	v_mov_b32_e32 v8, 0
	v_mov_b32_e32 v9, 0
	v_mov_b32_e32 v10, 0
	v_mov_b32_e32 v11, 0
	v_mov_b32_e32 v12, 0
	v_mov_b32_e32 v13, 0
	v_mov_b32_e32 v14, 0
	v_mov_b32_e32 v15, 0
	v_mov_b32_e32 v16, 0
	v_mov_b32_e32 v17, 0
	v_mov_b32_e32 v20, 0
	v_mov_b32_e32 v21, 0
	v_mov_b32_e32 v22, 0
	v_mov_b32_e32 v23, 0
	v_mov_b32_e32 v24, 0
	v_mov_b32_e32 v25, 0
	v_mov_b32_e32 v26, 0
	v_mov_b32_e32 v27, 0
	v_mov_b32_e32 v28, 0
	v_mov_b32_e32 v29, 0
	v_mov_b32_e32 v30, 0
	v_mov_b32_e32 v31, 0
	v_mov_b32_e32 v32, 0
	v_mov_b32_e32 v33, 0
	v_mov_b32_e32 v34, 0
	v_mov_b32_e32 v35, 0
	v_mov_b32_e32 v36, 0
	v_mov_b32_e32 v37, 0
	v_mov_b32_e32 v38, 0
	v_mov_b32_e32 v39, 0
	v_mov_b32_e32 v40, 0
	v_mov_b32_e32 v41, 0
	v_mov_b32_e32 v42, 0
	v_mov_b32_e32 v43, 0
	v_mov_b32_e32 v44, 0
	v_mov_b32_e32 v45, 0
	v_mov_b32_e32 v46, 0
	v_mov_b32_e32 v47, 0
	v_mov_b32_e32 v48, 0
	v_mov_b32_e32 v49, 0
	v_mov_b32_e32 v50, 0
	v_mov_b32_e32 v51, 0
	v_mov_b32_e32 v52, 0
	v_mov_b32_e32 v53, 0
	v_mov_b32_e32 v54, 0
	v_mov_b32_e32 v55, 0
	v_mov_b32_e32 v56, 0
	v_mov_b32_e32 v57, 0
	v_mov_b32_e32 v58, 0
	v_mov_b32_e32 v59, 0
	v_mov_b32_e32 v60, 0
	v_mov_b32_e32 v61, 0
	v_mov_b32_e32 v62, 0
	v_mov_b32_e32 v63, 0
	v_mov_b32_e32 v64, 0
	v_mov_b32_e32 v65, 0
	v_mov_b32_e32 v66, 0
	v_mov_b32_e32 v67, 0
	v_mov_b32_e32 v68, 0
	v_mov_b32_e32 v69, 0
	v_mov_b32_e32 v70, 0
	v_mov_b32_e32 v71, 0
	v_mov_b32_e32 v72, 0
	v_mov_b32_e32 v73, 0
	v_mov_b32_e32 v74, 0
	v_mov_b32_e32 v75, 0
	v_mov_b32_e32 v76, 0
	v_mov_b32_e32 v77, 0
	v_mov_b32_e32 v78, 0
	v_mov_b32_e32 v79, 0
	v_mov_b32_e32 v80, 0
	v_mov_b32_e32 v81, 0
	v_mov_b32_e32 v82, 0
	v_mov_b32_e32 v83, 0
	v_mov_b32_e32 v84, 0
	v_mov_b32_e32 v85, 0
	v_mov_b32_e32 v86, 0
	v_mov_b32_e32 v87, 0
	v_mov_b32_e32 v88, 0
	v_mov_b32_e32 v89, 0
	v_mov_b32_e32 v90, 0
	v_mov_b32_e32 v91, 0
	v_mov_b32_e32 v92, 0
	v_mov_b32_e32 v93, 0
	v_mov_b32_e32 v94, 0
	v_mov_b32_e32 v95, 0
	v_mov_b32_e32 v96, 0
	v_mov_b32_e32 v97, 0
	v_mov_b32_e32 v98, 0
	v_mov_b32_e32 v99, 0
	v_mov_b32_e32 v100, 0
	v_mov_b32_e32 v101, 0
	v_mov_b32_e32 v102, 0
	v_mov_b32_e32 v103, 0
	v_mov_b32_e32 v104, 0
	v_mov_b32_e32 v105, 0
	v_mov_b32_e32 v106, 0
	v_mov_b32_e32 v107, 0
	v_mov_b32_e32 v108, 0
	v_mov_b32_e32 v109, 0
	v_mov_b32_e32 v110, 0
	v_mov_b32_e32 v111, 0
	v_mov_b32_e32 v112, 0
	v_mov_b32_e32 v113, 0
	v_mov_b32_e32 v114, 0
	v_mov_b32_e32 v115, 0
	v_mov_b32_e32 v116, 0
	v_mov_b32_e32 v117, 0
	v_mov_b32_e32 v118, 0
	v_mov_b32_e32 v119, 0
	v_mov_b32_e32 v120, 0
	v_mov_b32_e32 v121, 0
	v_mov_b32_e32 v122, 0
	v_mov_b32_e32 v123, 0
	v_mov_b32_e32 v124, 0
	v_mov_b32_e32 v125, 0
	v_mov_b32_e32 v126, 0
	v_mov_b32_e32 v127, 0
	v_mov_b32_e32 v128, 0
	v_mov_b32_e32 v129, 0
	s_branch .LBB0_554

.LBB0_564:
	v_lshl_add_u32 v150, s21, 8, v141
	v_ashrrev_i32_e32 v151, 31, v150
	v_and_b32_e32 v249, 8, v228
	v_sub_u32_e32 v150, v150, v249
	s_and_b64 s[12:13], s[40:41], exec
	s_cselect_b32 s12, s48, s21
	v_lshl_add_u32 v238, s12, 8, v141
	v_mov_b32_e32 v239, 0
	v_lshl_add_u64 v[238:239], v[238:239], 2, s[4:5]
	s_mov_b64 s[12:13], 0x100000
	s_waitcnt vmcnt(8)
	v_fmamk_f32 v140, v240, 0x3a800000, v225
	v_rsq_f32_e32 v160, v140
	v_fmamk_f32 v144, v241, 0x3a800000, v225
	v_rsq_f32_e32 v158, v144
	v_fmamk_f32 v153, v244, 0x3a800000, v225
	v_pk_mul_f32 v[122:123], v[122:123], v[160:161] op_sel_hi:[1,0]
	v_pk_mul_f32 v[126:127], v[126:127], v[160:161] op_sel_hi:[1,0]
	v_pk_mul_f32 v[124:125], v[124:125], v[160:161] op_sel_hi:[1,0]
	v_max_f32_e32 v122, 0, v122
	v_pk_mul_f32 v[128:129], v[128:129], v[160:161] op_sel_hi:[1,0]
	v_max_f32_e32 v123, 0, v123
	v_max_f32_e32 v124, 0, v124
	v_max_f32_e32 v126, 0, v126
	v_max_f32_e32 v125, 0, v125
	v_pk_mul_f32 v[114:115], v[114:115], v[160:161] op_sel_hi:[1,0]
	v_mul_f32_e32 v126, v126, v126
	v_mul_f32_e32 v125, v125, v125
	v_pk_mul_f32 v[118:119], v[118:119], v[160:161] op_sel_hi:[1,0]
	v_pk_mul_f32 v[116:117], v[116:117], v[160:161] op_sel_hi:[1,0]
	v_max_f32_e32 v114, 0, v114
	v_pk_mul_f32 v[120:121], v[120:121], v[160:161] op_sel_hi:[1,0]
	v_max_f32_e32 v115, 0, v115
	v_max_f32_e32 v116, 0, v116
	v_max_f32_e32 v118, 0, v118
	v_max_f32_e32 v117, 0, v117
	v_mul_f32_e32 v118, v118, v118
	v_mul_f32_e32 v117, v117, v117
	v_pk_mul_f32 v[106:107], v[106:107], v[158:159] op_sel_hi:[1,0]
	v_pk_mul_f32 v[110:111], v[110:111], v[158:159] op_sel_hi:[1,0]
	v_pk_mul_f32 v[108:109], v[108:109], v[158:159] op_sel_hi:[1,0]
	v_max_f32_e32 v106, 0, v106
	v_pk_mul_f32 v[112:113], v[112:113], v[158:159] op_sel_hi:[1,0]
	v_max_f32_e32 v107, 0, v107
	v_max_f32_e32 v108, 0, v108
	v_fmamk_f32 v146, v242, 0x3a800000, v225
	v_max_f32_e32 v110, 0, v110
	v_max_f32_e32 v109, 0, v109
	v_pk_mul_f32 v[98:99], v[98:99], v[158:159] op_sel_hi:[1,0]
	v_rsq_f32_e32 v154, v146
	v_mul_f32_e32 v110, v110, v110
	v_mul_f32_e32 v109, v109, v109
	v_pk_mul_f32 v[102:103], v[102:103], v[158:159] op_sel_hi:[1,0]
	v_pk_mul_f32 v[100:101], v[100:101], v[158:159] op_sel_hi:[1,0]
	v_max_f32_e32 v98, 0, v98
	v_pk_mul_f32 v[104:105], v[104:105], v[158:159] op_sel_hi:[1,0]
	v_max_f32_e32 v99, 0, v99
	v_max_f32_e32 v100, 0, v100
	v_max_f32_e32 v102, 0, v102
	v_max_f32_e32 v101, 0, v101
	v_mul_f32_e32 v102, v102, v102
	v_mul_f32_e32 v101, v101, v101
	v_fmamk_f32 v148, v243, 0x3a800000, v225
	v_fmamk_f32 v155, v245, 0x3a800000, v225
	v_pk_mul_f32 v[90:91], v[90:91], v[154:155] op_sel_hi:[1,0]
	v_pk_mul_f32 v[94:95], v[94:95], v[154:155] op_sel_hi:[1,0]
	v_pk_mul_f32 v[92:93], v[92:93], v[154:155] op_sel_hi:[1,0]
	v_max_f32_e32 v90, 0, v90
	v_pk_mul_f32 v[96:97], v[96:97], v[154:155] op_sel_hi:[1,0]
	v_max_f32_e32 v91, 0, v91
	v_max_f32_e32 v92, 0, v92
	v_max_f32_e32 v94, 0, v94
	v_max_f32_e32 v93, 0, v93
	v_pk_mul_f32 v[82:83], v[82:83], v[154:155] op_sel_hi:[1,0]
	v_mul_f32_e32 v94, v94, v94
	v_mul_f32_e32 v93, v93, v93
	v_pk_mul_f32 v[86:87], v[86:87], v[154:155] op_sel_hi:[1,0]
	v_pk_mul_f32 v[84:85], v[84:85], v[154:155] op_sel_hi:[1,0]
	v_max_f32_e32 v82, 0, v82
	v_pk_mul_f32 v[88:89], v[88:89], v[154:155] op_sel_hi:[1,0]
	v_max_f32_e32 v83, 0, v83
	v_max_f32_e32 v84, 0, v84
	v_max_f32_e32 v86, 0, v86
	v_max_f32_e32 v85, 0, v85
	v_mul_f32_e32 v86, v86, v86
	v_mul_f32_e32 v85, v85, v85
	v_rsq_f32_e32 v146, v155
	v_fmamk_f32 v156, v246, 0x3a800000, v225
	v_rsq_f32_e32 v144, v156
	v_fmamk_f32 v142, v247, 0x3a800000, v225
	v_rsq_f32_e32 v140, v142
	global_load_dword v240, v[238:239], off
	global_load_dword v241, v[238:239], off offset:64
	global_load_dword v242, v[238:239], off offset:128
	global_load_dword v243, v[238:239], off offset:192
	global_load_dword v244, v[238:239], off offset:512
	global_load_dword v245, v[238:239], off offset:576
	global_load_dword v246, v[238:239], off offset:640
	global_load_dword v247, v[238:239], off offset:704
	v_lshl_or_b32 v142, s20, 8, v147
	v_lshl_add_u32 v142, v249, 2, v142
	v_bfe_u32 v250, v224, 6, 2
	v_lshl_add_u32 v142, v250, 5, v142
	v_ashrrev_i32_e32 v143, 31, v142
	v_lshlrev_b64 v[156:157], 13, v[150:151]
	v_mul_f32_e32 v151, v122, v122
	v_max_f32_e32 v122, 0, v127
	v_lshl_add_u64 v[162:163], s[42:43], 0, v[156:157]
	v_lshlrev_b64 v[156:157], 1, v[142:143]
	v_mul_f32_e32 v122, v122, v122
	v_mul_f32_e32 v127, v123, v123
	v_max_f32_e32 v123, 0, v128
	v_mul_f32_e32 v128, v124, v124
	v_max_f32_e32 v124, 0, v129
	v_mov_b32_e32 v129, 0
	v_lshl_add_u64 v[142:143], v[162:163], 0, v[156:157]
	v_mul_f32_e32 v123, v123, v123
	v_mul_f32_e32 v124, v124, v124
	v_cvt_pk_bf16_f32 v122, v126, v122
	v_mov_b32_e32 v126, 0
	v_cvt_pk_bf16_f32 v123, v123, v124
	v_cvt_pk_bf16_f32 v124, v151, v127
	v_mov_b32_e32 v127, 0
	v_cvt_pk_bf16_f32 v125, v128, v125
	v_mov_b32_e32 v128, 0
	v_mov_b32_e32 v248, v122
	v_mov_b32_e32 v249, v123
	v_mov_b32_e32 v250, v124
	v_mov_b32_e32 v251, v125
	v_rsq_f32_e32 v152, v148
	v_rsq_f32_e32 v148, v153
	v_mov_b32_e32 v123, 0
	v_mov_b32_e32 v124, 0
	v_mov_b32_e32 v125, 0
	v_mul_f32_e32 v122, v114, v114
	v_max_f32_e32 v114, 0, v119
	v_mul_f32_e32 v114, v114, v114
	v_mul_f32_e32 v119, v115, v115
	v_max_f32_e32 v115, 0, v120
	v_mul_f32_e32 v120, v116, v116
	v_max_f32_e32 v116, 0, v121
	v_mov_b32_e32 v121, 0
	v_mul_f32_e32 v115, v115, v115
	v_mul_f32_e32 v116, v116, v116
	v_cvt_pk_bf16_f32 v114, v118, v114
	v_mov_b32_e32 v118, 0
	v_cvt_pk_bf16_f32 v115, v115, v116
	v_cvt_pk_bf16_f32 v116, v122, v119
	v_mov_b32_e32 v119, 0
	v_mov_b32_e32 v122, 0
	v_cvt_pk_bf16_f32 v117, v120, v117
	v_mov_b32_e32 v120, 0
	v_mov_b32_dpp v252, v248 row_ror:8 row_mask:0xf bank_mask:0xf
	v_mov_b32_dpp v226, v114 row_ror:8 row_mask:0xf bank_mask:0xf
	v_cndmask_b32_e64 v114, v114, v252, s[98:99]
	v_cndmask_b32_e64 v248, v226, v248, s[98:99]
	v_mov_b32_dpp v252, v249 row_ror:8 row_mask:0xf bank_mask:0xf
	v_mov_b32_dpp v226, v115 row_ror:8 row_mask:0xf bank_mask:0xf
	v_cndmask_b32_e64 v115, v115, v252, s[98:99]
	v_cndmask_b32_e64 v249, v226, v249, s[98:99]
	v_mov_b32_dpp v252, v250 row_ror:8 row_mask:0xf bank_mask:0xf
	v_mov_b32_dpp v226, v116 row_ror:8 row_mask:0xf bank_mask:0xf
	v_cndmask_b32_e64 v116, v116, v252, s[98:99]
	v_cndmask_b32_e64 v250, v226, v250, s[98:99]
	v_mov_b32_dpp v252, v251 row_ror:8 row_mask:0xf bank_mask:0xf
	v_mov_b32_dpp v226, v117 row_ror:8 row_mask:0xf bank_mask:0xf
	v_cndmask_b32_e64 v117, v117, v252, s[98:99]
	v_cndmask_b32_e64 v251, v226, v251, s[98:99]
	v_lshl_add_u64 v[226:227], v[142:143], 0, s[100:101]
	flat_store_dwordx4 v[142:143], v[248:251] nt
	flat_store_dwordx4 v[226:227], v[114:117] nt
	v_pk_mul_f32 v[74:75], v[74:75], v[152:153] op_sel_hi:[1,0]
	v_pk_mul_f32 v[78:79], v[78:79], v[152:153] op_sel_hi:[1,0]
	v_mov_b32_e32 v117, 0
	v_or_b32_e32 v114, 16, v150
	v_ashrrev_i32_e32 v115, 31, v114
	v_lshlrev_b64 v[114:115], 13, v[114:115]
	v_mul_f32_e32 v116, v106, v106
	v_max_f32_e32 v106, 0, v111
	v_lshl_add_u64 v[114:115], s[42:43], 0, v[114:115]
	v_mul_f32_e32 v106, v106, v106
	v_mul_f32_e32 v111, v107, v107
	v_max_f32_e32 v107, 0, v112
	v_mul_f32_e32 v112, v108, v108
	v_max_f32_e32 v108, 0, v113
	v_mov_b32_e32 v113, 0
	v_lshl_add_u64 v[114:115], v[114:115], 0, v[156:157]
	v_mul_f32_e32 v107, v107, v107
	v_mul_f32_e32 v108, v108, v108
	v_cvt_pk_bf16_f32 v106, v110, v106
	v_mov_b32_e32 v110, 0
	v_cvt_pk_bf16_f32 v107, v107, v108
	v_cvt_pk_bf16_f32 v108, v116, v111
	v_mov_b32_e32 v111, 0
	v_mov_b32_e32 v116, 0
	v_cvt_pk_bf16_f32 v109, v112, v109
	v_mov_b32_e32 v112, 0
	v_mov_b32_e32 v248, v106
	v_mov_b32_e32 v249, v107
	v_mov_b32_e32 v250, v108
	v_mov_b32_e32 v251, v109
	v_pk_mul_f32 v[76:77], v[76:77], v[152:153] op_sel_hi:[1,0]
	v_max_f32_e32 v74, 0, v74
	v_mov_b32_e32 v107, 0
	v_mov_b32_e32 v108, 0
	v_mov_b32_e32 v109, 0
	v_mul_f32_e32 v106, v98, v98
	v_max_f32_e32 v98, 0, v103
	v_mul_f32_e32 v98, v98, v98
	v_mul_f32_e32 v103, v99, v99
	v_max_f32_e32 v99, 0, v104
	v_mul_f32_e32 v104, v100, v100
	v_max_f32_e32 v100, 0, v105
	v_mov_b32_e32 v105, 0
	v_mul_f32_e32 v99, v99, v99
	v_mul_f32_e32 v100, v100, v100
	v_cvt_pk_bf16_f32 v98, v102, v98
	v_mov_b32_e32 v102, 0
	v_cvt_pk_bf16_f32 v99, v99, v100
	v_cvt_pk_bf16_f32 v100, v106, v103
	v_mov_b32_e32 v103, 0
	v_mov_b32_e32 v106, 0
	v_cvt_pk_bf16_f32 v101, v104, v101
	v_mov_b32_e32 v104, 0
	v_mov_b32_dpp v252, v248 row_ror:8 row_mask:0xf bank_mask:0xf
	v_mov_b32_dpp v226, v98 row_ror:8 row_mask:0xf bank_mask:0xf
	v_cndmask_b32_e64 v98, v98, v252, s[98:99]
	v_cndmask_b32_e64 v248, v226, v248, s[98:99]
	v_mov_b32_dpp v252, v249 row_ror:8 row_mask:0xf bank_mask:0xf
	v_mov_b32_dpp v226, v99 row_ror:8 row_mask:0xf bank_mask:0xf
	v_cndmask_b32_e64 v99, v99, v252, s[98:99]
	v_cndmask_b32_e64 v249, v226, v249, s[98:99]
	v_mov_b32_dpp v252, v250 row_ror:8 row_mask:0xf bank_mask:0xf
	v_mov_b32_dpp v226, v100 row_ror:8 row_mask:0xf bank_mask:0xf
	v_cndmask_b32_e64 v100, v100, v252, s[98:99]
	v_cndmask_b32_e64 v250, v226, v250, s[98:99]
	v_mov_b32_dpp v252, v251 row_ror:8 row_mask:0xf bank_mask:0xf
	v_mov_b32_dpp v226, v101 row_ror:8 row_mask:0xf bank_mask:0xf
	v_cndmask_b32_e64 v101, v101, v252, s[98:99]
	v_cndmask_b32_e64 v251, v226, v251, s[98:99]
	v_lshl_add_u64 v[226:227], v[114:115], 0, s[100:101]
	flat_store_dwordx4 v[114:115], v[248:251] nt
	flat_store_dwordx4 v[226:227], v[98:101] nt
	v_pk_mul_f32 v[80:81], v[80:81], v[152:153] op_sel_hi:[1,0]
	v_max_f32_e32 v75, 0, v75
	v_mov_b32_e32 v101, 0
	v_mov_b32_e32 v114, 0
	v_mov_b32_e32 v115, 0
	v_or_b32_e32 v98, 32, v150
	v_ashrrev_i32_e32 v99, 31, v98
	v_lshlrev_b64 v[98:99], 13, v[98:99]
	v_mul_f32_e32 v100, v90, v90
	v_max_f32_e32 v90, 0, v95
	v_lshl_add_u64 v[98:99], s[42:43], 0, v[98:99]
	v_mul_f32_e32 v90, v90, v90
	v_mul_f32_e32 v95, v91, v91
	v_max_f32_e32 v91, 0, v96
	v_mul_f32_e32 v96, v92, v92
	v_max_f32_e32 v92, 0, v97
	v_mov_b32_e32 v97, 0
	v_lshl_add_u64 v[98:99], v[98:99], 0, v[156:157]
	v_mul_f32_e32 v91, v91, v91
	v_mul_f32_e32 v92, v92, v92
	v_cvt_pk_bf16_f32 v90, v94, v90
	v_mov_b32_e32 v94, 0
	v_cvt_pk_bf16_f32 v91, v91, v92
	v_cvt_pk_bf16_f32 v92, v100, v95
	v_mov_b32_e32 v95, 0
	v_mov_b32_e32 v100, 0
	v_cvt_pk_bf16_f32 v93, v96, v93
	v_mov_b32_e32 v96, 0
	v_mov_b32_e32 v248, v90
	v_mov_b32_e32 v249, v91
	v_mov_b32_e32 v250, v92
	v_mov_b32_e32 v251, v93
	v_max_f32_e32 v76, 0, v76
	v_max_f32_e32 v78, 0, v78
	v_mov_b32_e32 v91, 0
	v_mov_b32_e32 v92, 0
	v_mov_b32_e32 v93, 0
	v_mul_f32_e32 v90, v82, v82
	v_max_f32_e32 v82, 0, v87
	v_mul_f32_e32 v82, v82, v82
	v_mul_f32_e32 v87, v83, v83
	v_max_f32_e32 v83, 0, v88
	v_mul_f32_e32 v88, v84, v84
	v_max_f32_e32 v84, 0, v89
	v_mov_b32_e32 v89, 0
	v_mul_f32_e32 v83, v83, v83
	v_mul_f32_e32 v84, v84, v84
	v_cvt_pk_bf16_f32 v82, v86, v82
	v_mov_b32_e32 v86, 0
	v_cvt_pk_bf16_f32 v83, v83, v84
	v_cvt_pk_bf16_f32 v84, v90, v87
	v_mov_b32_e32 v87, 0
	v_mov_b32_e32 v90, 0
	v_cvt_pk_bf16_f32 v85, v88, v85
	v_mov_b32_e32 v88, 0
	v_mov_b32_dpp v252, v248 row_ror:8 row_mask:0xf bank_mask:0xf
	v_mov_b32_dpp v226, v82 row_ror:8 row_mask:0xf bank_mask:0xf
	v_cndmask_b32_e64 v82, v82, v252, s[98:99]
	v_cndmask_b32_e64 v248, v226, v248, s[98:99]
	v_mov_b32_dpp v252, v249 row_ror:8 row_mask:0xf bank_mask:0xf
	v_mov_b32_dpp v226, v83 row_ror:8 row_mask:0xf bank_mask:0xf
	v_cndmask_b32_e64 v83, v83, v252, s[98:99]
	v_cndmask_b32_e64 v249, v226, v249, s[98:99]
	v_mov_b32_dpp v252, v250 row_ror:8 row_mask:0xf bank_mask:0xf
	v_mov_b32_dpp v226, v84 row_ror:8 row_mask:0xf bank_mask:0xf
	v_cndmask_b32_e64 v84, v84, v252, s[98:99]
	v_cndmask_b32_e64 v250, v226, v250, s[98:99]
	v_mov_b32_dpp v252, v251 row_ror:8 row_mask:0xf bank_mask:0xf
	v_mov_b32_dpp v226, v85 row_ror:8 row_mask:0xf bank_mask:0xf
	v_cndmask_b32_e64 v85, v85, v252, s[98:99]
	v_cndmask_b32_e64 v251, v226, v251, s[98:99]
	v_lshl_add_u64 v[226:227], v[98:99], 0, s[100:101]
	flat_store_dwordx4 v[98:99], v[248:251] nt
	flat_store_dwordx4 v[226:227], v[82:85] nt
	v_max_f32_e32 v77, 0, v77
	v_pk_mul_f32 v[68:69], v[68:69], v[152:153] op_sel_hi:[1,0]
	v_mov_b32_e32 v85, 0
	v_mov_b32_e32 v98, 0
	v_mov_b32_e32 v99, 0
	v_or_b32_e32 v82, 48, v150
	v_ashrrev_i32_e32 v83, 31, v82
	v_lshlrev_b64 v[82:83], 13, v[82:83]
	v_mul_f32_e32 v84, v74, v74
	v_max_f32_e32 v74, 0, v79
	v_lshl_add_u64 v[82:83], s[42:43], 0, v[82:83]
	v_mul_f32_e32 v74, v74, v74
	v_mul_f32_e32 v79, v75, v75
	v_max_f32_e32 v75, 0, v80
	v_mul_f32_e32 v80, v76, v76
	v_max_f32_e32 v76, 0, v81
	v_mov_b32_e32 v81, 0
	v_pk_mul_f32 v[66:67], v[66:67], v[152:153] op_sel_hi:[1,0]
	v_lshl_add_u64 v[82:83], v[82:83], 0, v[156:157]
	v_mul_f32_e32 v78, v78, v78
	v_mul_f32_e32 v75, v75, v75
	v_mul_f32_e32 v76, v76, v76
	v_mul_f32_e32 v77, v77, v77
	v_cvt_pk_bf16_f32 v74, v78, v74
	v_mov_b32_e32 v78, 0
	v_pk_mul_f32 v[72:73], v[72:73], v[152:153] op_sel_hi:[1,0]
	v_pk_mul_f32 v[70:71], v[70:71], v[152:153] op_sel_hi:[1,0]
	v_max_f32_e32 v66, 0, v66
	v_max_f32_e32 v67, 0, v67
	v_max_f32_e32 v68, 0, v68
	v_cvt_pk_bf16_f32 v75, v75, v76
	v_cvt_pk_bf16_f32 v76, v84, v79
	v_mov_b32_e32 v79, 0
	v_mov_b32_e32 v84, 0
	v_cvt_pk_bf16_f32 v77, v80, v77
	v_mov_b32_e32 v80, 0
	v_mov_b32_e32 v248, v74
	v_mov_b32_e32 v249, v75
	v_mov_b32_e32 v250, v76
	v_mov_b32_e32 v251, v77
	v_max_f32_e32 v70, 0, v70
	v_max_f32_e32 v69, 0, v69
	v_mov_b32_e32 v75, 0
	v_mov_b32_e32 v76, 0
	v_mov_b32_e32 v77, 0
	v_mul_f32_e32 v74, v66, v66
	v_max_f32_e32 v66, 0, v71
	v_mul_f32_e32 v71, v67, v67
	v_max_f32_e32 v67, 0, v72
	v_mul_f32_e32 v72, v68, v68
	v_max_f32_e32 v68, 0, v73
	v_mov_b32_e32 v73, 0
	v_mul_f32_e32 v66, v66, v66
	v_mul_f32_e32 v67, v67, v67
	v_mul_f32_e32 v68, v68, v68
	v_pk_mul_f32 v[58:59], v[58:59], v[148:149] op_sel_hi:[1,0]
	v_mul_f32_e32 v70, v70, v70
	v_mul_f32_e32 v69, v69, v69
	v_cvt_pk_bf16_f32 v66, v70, v66
	v_mov_b32_e32 v70, 0
	v_cvt_pk_bf16_f32 v67, v67, v68
	v_cvt_pk_bf16_f32 v68, v74, v71
	v_mov_b32_e32 v71, 0
	v_mov_b32_e32 v74, 0
	v_pk_mul_f32 v[62:63], v[62:63], v[148:149] op_sel_hi:[1,0]
	v_pk_mul_f32 v[60:61], v[60:61], v[148:149] op_sel_hi:[1,0]
	v_max_f32_e32 v58, 0, v58
	v_cvt_pk_bf16_f32 v69, v72, v69
	v_mov_b32_e32 v72, 0
	v_mov_b32_dpp v252, v248 row_ror:8 row_mask:0xf bank_mask:0xf
	v_mov_b32_dpp v226, v66 row_ror:8 row_mask:0xf bank_mask:0xf
	v_cndmask_b32_e64 v66, v66, v252, s[98:99]
	v_cndmask_b32_e64 v248, v226, v248, s[98:99]
	v_mov_b32_dpp v252, v249 row_ror:8 row_mask:0xf bank_mask:0xf
	v_mov_b32_dpp v226, v67 row_ror:8 row_mask:0xf bank_mask:0xf
	v_cndmask_b32_e64 v67, v67, v252, s[98:99]
	v_cndmask_b32_e64 v249, v226, v249, s[98:99]
	v_mov_b32_dpp v252, v250 row_ror:8 row_mask:0xf bank_mask:0xf
	v_mov_b32_dpp v226, v68 row_ror:8 row_mask:0xf bank_mask:0xf
	v_cndmask_b32_e64 v68, v68, v252, s[98:99]
	v_cndmask_b32_e64 v250, v226, v250, s[98:99]
	v_mov_b32_dpp v252, v251 row_ror:8 row_mask:0xf bank_mask:0xf
	v_mov_b32_dpp v226, v69 row_ror:8 row_mask:0xf bank_mask:0xf
	v_cndmask_b32_e64 v69, v69, v252, s[98:99]
	v_cndmask_b32_e64 v251, v226, v251, s[98:99]
	v_lshl_add_u64 v[226:227], v[82:83], 0, s[100:101]
	flat_store_dwordx4 v[82:83], v[248:251] nt
	flat_store_dwordx4 v[226:227], v[66:69] nt
	v_pk_mul_f32 v[64:65], v[64:65], v[148:149] op_sel_hi:[1,0]
	v_max_f32_e32 v62, 0, v62
	v_mov_b32_e32 v69, 0
	v_mov_b32_e32 v82, 0
	v_mov_b32_e32 v83, 0
	v_mul_f32_e32 v68, v58, v58
	v_max_f32_e32 v58, 0, v63
	v_max_f32_e32 v59, 0, v59
	v_max_f32_e32 v60, 0, v60
	v_lshl_add_u64 v[66:67], v[142:143], 0, s[12:13]
	v_mul_f32_e32 v62, v62, v62
	v_mul_f32_e32 v58, v58, v58
	v_mul_f32_e32 v63, v59, v59
	v_max_f32_e32 v59, 0, v64
	v_mul_f32_e32 v64, v60, v60
	v_max_f32_e32 v60, 0, v65
	v_mov_b32_e32 v65, 0
	s_mov_b32 s12, 0x100000
	v_mul_f32_e32 v59, v59, v59
	v_max_f32_e32 v61, 0, v61
	v_mul_f32_e32 v60, v60, v60
	v_cvt_pk_bf16_f32 v58, v62, v58
	v_add_co_u32_e32 v62, vcc, s12, v142
	v_pk_mul_f32 v[52:53], v[52:53], v[148:149] op_sel_hi:[1,0]
	v_pk_mul_f32 v[50:51], v[50:51], v[148:149] op_sel_hi:[1,0]
	v_mul_f32_e32 v61, v61, v61
	v_cvt_pk_bf16_f32 v59, v59, v60
	v_cvt_pk_bf16_f32 v60, v68, v63
	v_mov_b32_e32 v68, 0
	v_addc_co_u32_e32 v63, vcc, 0, v143, vcc
	v_pk_mul_f32 v[56:57], v[56:57], v[148:149] op_sel_hi:[1,0]
	v_pk_mul_f32 v[54:55], v[54:55], v[148:149] op_sel_hi:[1,0]
	v_max_f32_e32 v50, 0, v50
	v_max_f32_e32 v51, 0, v51
	v_max_f32_e32 v52, 0, v52
	v_cvt_pk_bf16_f32 v61, v64, v61
	v_mov_b32_e32 v64, 0
	v_mov_b32_e32 v248, v58
	v_mov_b32_e32 v249, v59
	v_mov_b32_e32 v250, v60
	v_mov_b32_e32 v251, v61
	v_max_f32_e32 v54, 0, v54
	v_max_f32_e32 v53, 0, v53
	v_mov_b32_e32 v59, 0
	v_mov_b32_e32 v60, 0
	v_mov_b32_e32 v61, 0
	v_mov_b32_e32 v62, 0
	v_mov_b32_e32 v63, 0
	v_mul_f32_e32 v58, v50, v50
	v_max_f32_e32 v50, 0, v55
	v_mul_f32_e32 v55, v51, v51
	v_max_f32_e32 v51, 0, v56
	v_mul_f32_e32 v56, v52, v52
	v_max_f32_e32 v52, 0, v57
	v_mov_b32_e32 v57, 0
	v_mul_f32_e32 v50, v50, v50
	v_mul_f32_e32 v51, v51, v51
	v_mul_f32_e32 v52, v52, v52
	v_pk_mul_f32 v[42:43], v[42:43], v[146:147] op_sel_hi:[1,0]
	v_mul_f32_e32 v54, v54, v54
	v_mul_f32_e32 v53, v53, v53
	v_cvt_pk_bf16_f32 v50, v54, v50
	v_mov_b32_e32 v54, 0
	v_cvt_pk_bf16_f32 v51, v51, v52
	v_cvt_pk_bf16_f32 v52, v58, v55
	v_mov_b32_e32 v55, 0
	v_mov_b32_e32 v58, 0
	v_pk_mul_f32 v[46:47], v[46:47], v[146:147] op_sel_hi:[1,0]
	v_pk_mul_f32 v[44:45], v[44:45], v[146:147] op_sel_hi:[1,0]
	v_max_f32_e32 v42, 0, v42
	v_cvt_pk_bf16_f32 v53, v56, v53
	v_mov_b32_e32 v56, 0
	v_mov_b32_dpp v252, v248 row_ror:8 row_mask:0xf bank_mask:0xf
	v_mov_b32_dpp v226, v50 row_ror:8 row_mask:0xf bank_mask:0xf
	v_cndmask_b32_e64 v50, v50, v252, s[98:99]
	v_cndmask_b32_e64 v248, v226, v248, s[98:99]
	v_mov_b32_dpp v252, v249 row_ror:8 row_mask:0xf bank_mask:0xf
	v_mov_b32_dpp v226, v51 row_ror:8 row_mask:0xf bank_mask:0xf
	v_cndmask_b32_e64 v51, v51, v252, s[98:99]
	v_cndmask_b32_e64 v249, v226, v249, s[98:99]
	v_mov_b32_dpp v252, v250 row_ror:8 row_mask:0xf bank_mask:0xf
	v_mov_b32_dpp v226, v52 row_ror:8 row_mask:0xf bank_mask:0xf
	v_cndmask_b32_e64 v52, v52, v252, s[98:99]
	v_cndmask_b32_e64 v250, v226, v250, s[98:99]
	v_mov_b32_dpp v252, v251 row_ror:8 row_mask:0xf bank_mask:0xf
	v_mov_b32_dpp v226, v53 row_ror:8 row_mask:0xf bank_mask:0xf
	v_cndmask_b32_e64 v53, v53, v252, s[98:99]
	v_cndmask_b32_e64 v251, v226, v251, s[98:99]
	v_lshl_add_u64 v[226:227], v[66:67], 0, s[100:101]
	flat_store_dwordx4 v[66:67], v[248:251] nt
	flat_store_dwordx4 v[226:227], v[50:53] nt
	s_mov_b64 s[12:13], 0x120000
	v_pk_mul_f32 v[48:49], v[48:49], v[146:147] op_sel_hi:[1,0]
	v_mov_b32_e32 v53, 0
	v_mov_b32_e32 v66, 0
	v_mov_b32_e32 v67, 0
	v_max_f32_e32 v46, 0, v46
	v_mul_f32_e32 v52, v42, v42
	v_max_f32_e32 v42, 0, v47
	v_max_f32_e32 v43, 0, v43
	v_max_f32_e32 v44, 0, v44
	v_lshl_add_u64 v[50:51], v[142:143], 0, s[12:13]
	v_mul_f32_e32 v46, v46, v46
	v_mul_f32_e32 v42, v42, v42
	v_mul_f32_e32 v47, v43, v43
	v_max_f32_e32 v43, 0, v48
	v_mul_f32_e32 v48, v44, v44
	v_max_f32_e32 v44, 0, v49
	v_mov_b32_e32 v49, 0
	s_mov_b32 s12, 0x120000
	v_mul_f32_e32 v43, v43, v43
	v_max_f32_e32 v45, 0, v45
	v_mul_f32_e32 v44, v44, v44
	v_cvt_pk_bf16_f32 v42, v46, v42
	v_add_co_u32_e32 v46, vcc, s12, v142
	v_pk_mul_f32 v[36:37], v[36:37], v[146:147] op_sel_hi:[1,0]
	v_pk_mul_f32 v[34:35], v[34:35], v[146:147] op_sel_hi:[1,0]
	v_mul_f32_e32 v45, v45, v45
	v_cvt_pk_bf16_f32 v43, v43, v44
	v_cvt_pk_bf16_f32 v44, v52, v47
	v_mov_b32_e32 v52, 0
	v_addc_co_u32_e32 v47, vcc, 0, v143, vcc
	v_pk_mul_f32 v[40:41], v[40:41], v[146:147] op_sel_hi:[1,0]
	v_pk_mul_f32 v[38:39], v[38:39], v[146:147] op_sel_hi:[1,0]
	v_max_f32_e32 v34, 0, v34
	v_max_f32_e32 v35, 0, v35
	v_max_f32_e32 v36, 0, v36
	v_cvt_pk_bf16_f32 v45, v48, v45
	v_mov_b32_e32 v48, 0
	v_mov_b32_e32 v248, v42
	v_mov_b32_e32 v249, v43
	v_mov_b32_e32 v250, v44
	v_mov_b32_e32 v251, v45
	v_max_f32_e32 v38, 0, v38
	v_max_f32_e32 v37, 0, v37
	v_mov_b32_e32 v43, 0
	v_mov_b32_e32 v44, 0
	v_mov_b32_e32 v45, 0
	v_mov_b32_e32 v46, 0
	v_mov_b32_e32 v47, 0
	v_mul_f32_e32 v42, v34, v34
	v_max_f32_e32 v34, 0, v39
	v_mul_f32_e32 v39, v35, v35
	v_max_f32_e32 v35, 0, v40
	v_mul_f32_e32 v40, v36, v36
	v_max_f32_e32 v36, 0, v41
	v_mov_b32_e32 v41, 0
	v_mul_f32_e32 v34, v34, v34
	v_mul_f32_e32 v35, v35, v35
	v_mul_f32_e32 v36, v36, v36
	v_pk_mul_f32 v[26:27], v[26:27], v[144:145] op_sel_hi:[1,0]
	v_mul_f32_e32 v38, v38, v38
	v_mul_f32_e32 v37, v37, v37
	v_cvt_pk_bf16_f32 v34, v38, v34
	v_mov_b32_e32 v38, 0
	v_cvt_pk_bf16_f32 v35, v35, v36
	v_cvt_pk_bf16_f32 v36, v42, v39
	v_mov_b32_e32 v39, 0
	v_mov_b32_e32 v42, 0
	v_pk_mul_f32 v[30:31], v[30:31], v[144:145] op_sel_hi:[1,0]
	v_pk_mul_f32 v[28:29], v[28:29], v[144:145] op_sel_hi:[1,0]
	v_max_f32_e32 v26, 0, v26
	v_cvt_pk_bf16_f32 v37, v40, v37
	v_mov_b32_e32 v40, 0
	v_mov_b32_dpp v252, v248 row_ror:8 row_mask:0xf bank_mask:0xf
	v_mov_b32_dpp v226, v34 row_ror:8 row_mask:0xf bank_mask:0xf
	v_cndmask_b32_e64 v34, v34, v252, s[98:99]
	v_cndmask_b32_e64 v248, v226, v248, s[98:99]
	v_mov_b32_dpp v252, v249 row_ror:8 row_mask:0xf bank_mask:0xf
	v_mov_b32_dpp v226, v35 row_ror:8 row_mask:0xf bank_mask:0xf
	v_cndmask_b32_e64 v35, v35, v252, s[98:99]
	v_cndmask_b32_e64 v249, v226, v249, s[98:99]
	v_mov_b32_dpp v252, v250 row_ror:8 row_mask:0xf bank_mask:0xf
	v_mov_b32_dpp v226, v36 row_ror:8 row_mask:0xf bank_mask:0xf
	v_cndmask_b32_e64 v36, v36, v252, s[98:99]
	v_cndmask_b32_e64 v250, v226, v250, s[98:99]
	v_mov_b32_dpp v252, v251 row_ror:8 row_mask:0xf bank_mask:0xf
	v_mov_b32_dpp v226, v37 row_ror:8 row_mask:0xf bank_mask:0xf
	v_cndmask_b32_e64 v37, v37, v252, s[98:99]
	v_cndmask_b32_e64 v251, v226, v251, s[98:99]
	v_lshl_add_u64 v[226:227], v[50:51], 0, s[100:101]
	flat_store_dwordx4 v[50:51], v[248:251] nt
	flat_store_dwordx4 v[226:227], v[34:37] nt
	s_mov_b64 s[12:13], 0x140000
	v_pk_mul_f32 v[32:33], v[32:33], v[144:145] op_sel_hi:[1,0]
	v_mov_b32_e32 v37, 0
	v_mov_b32_e32 v50, 0
	v_mov_b32_e32 v51, 0
	v_max_f32_e32 v30, 0, v30
	v_mul_f32_e32 v36, v26, v26
	v_max_f32_e32 v26, 0, v31
	v_max_f32_e32 v27, 0, v27
	v_max_f32_e32 v28, 0, v28
	v_lshl_add_u64 v[34:35], v[142:143], 0, s[12:13]
	v_mul_f32_e32 v30, v30, v30
	v_mul_f32_e32 v26, v26, v26
	v_mul_f32_e32 v31, v27, v27
	v_max_f32_e32 v27, 0, v32
	v_mul_f32_e32 v32, v28, v28
	v_max_f32_e32 v28, 0, v33
	v_mov_b32_e32 v33, 0
	s_mov_b32 s12, 0x140000
	v_mul_f32_e32 v27, v27, v27
	v_max_f32_e32 v29, 0, v29
	v_mul_f32_e32 v28, v28, v28
	v_cvt_pk_bf16_f32 v26, v30, v26
	v_add_co_u32_e32 v30, vcc, s12, v142
	v_pk_mul_f32 v[20:21], v[20:21], v[144:145] op_sel_hi:[1,0]
	v_pk_mul_f32 v[18:19], v[18:19], v[144:145] op_sel_hi:[1,0]
	v_mul_f32_e32 v29, v29, v29
	v_cvt_pk_bf16_f32 v27, v27, v28
	v_cvt_pk_bf16_f32 v28, v36, v31
	v_mov_b32_e32 v36, 0
	v_addc_co_u32_e32 v31, vcc, 0, v143, vcc
	v_pk_mul_f32 v[24:25], v[24:25], v[144:145] op_sel_hi:[1,0]
	v_pk_mul_f32 v[22:23], v[22:23], v[144:145] op_sel_hi:[1,0]
	v_max_f32_e32 v18, 0, v18
	v_max_f32_e32 v19, 0, v19
	v_max_f32_e32 v20, 0, v20
	v_cvt_pk_bf16_f32 v29, v32, v29
	v_mov_b32_e32 v32, 0
	v_mov_b32_e32 v248, v26
	v_mov_b32_e32 v249, v27
	v_mov_b32_e32 v250, v28
	v_mov_b32_e32 v251, v29
	v_max_f32_e32 v22, 0, v22
	v_max_f32_e32 v21, 0, v21
	v_mov_b32_e32 v27, 0
	v_mov_b32_e32 v28, 0
	v_mov_b32_e32 v29, 0
	v_mov_b32_e32 v30, 0
	v_mov_b32_e32 v31, 0
	v_mul_f32_e32 v26, v18, v18
	v_max_f32_e32 v18, 0, v23
	v_mul_f32_e32 v23, v19, v19
	v_max_f32_e32 v19, 0, v24
	v_mul_f32_e32 v24, v20, v20
	v_max_f32_e32 v20, 0, v25
	v_mov_b32_e32 v25, 0
	v_mul_f32_e32 v18, v18, v18
	v_mul_f32_e32 v19, v19, v19
	v_mul_f32_e32 v20, v20, v20
	v_pk_mul_f32 v[10:11], v[10:11], v[140:141] op_sel_hi:[1,0]
	v_mul_f32_e32 v22, v22, v22
	v_mul_f32_e32 v21, v21, v21
	v_cvt_pk_bf16_f32 v18, v22, v18
	v_mov_b32_e32 v22, 0
	v_cvt_pk_bf16_f32 v19, v19, v20
	v_cvt_pk_bf16_f32 v20, v26, v23
	v_mov_b32_e32 v23, 0
	v_mov_b32_e32 v26, 0
	v_pk_mul_f32 v[14:15], v[14:15], v[140:141] op_sel_hi:[1,0]
	v_pk_mul_f32 v[12:13], v[12:13], v[140:141] op_sel_hi:[1,0]
	v_max_f32_e32 v10, 0, v10
	v_cvt_pk_bf16_f32 v21, v24, v21
	v_mov_b32_e32 v24, 0
	v_mov_b32_dpp v252, v248 row_ror:8 row_mask:0xf bank_mask:0xf
	v_mov_b32_dpp v226, v18 row_ror:8 row_mask:0xf bank_mask:0xf
	v_cndmask_b32_e64 v18, v18, v252, s[98:99]
	v_cndmask_b32_e64 v248, v226, v248, s[98:99]
	v_mov_b32_dpp v252, v249 row_ror:8 row_mask:0xf bank_mask:0xf
	v_mov_b32_dpp v226, v19 row_ror:8 row_mask:0xf bank_mask:0xf
	v_cndmask_b32_e64 v19, v19, v252, s[98:99]
	v_cndmask_b32_e64 v249, v226, v249, s[98:99]
	v_mov_b32_dpp v252, v250 row_ror:8 row_mask:0xf bank_mask:0xf
	v_mov_b32_dpp v226, v20 row_ror:8 row_mask:0xf bank_mask:0xf
	v_cndmask_b32_e64 v20, v20, v252, s[98:99]
	v_cndmask_b32_e64 v250, v226, v250, s[98:99]
	v_mov_b32_dpp v252, v251 row_ror:8 row_mask:0xf bank_mask:0xf
	v_mov_b32_dpp v226, v21 row_ror:8 row_mask:0xf bank_mask:0xf
	v_cndmask_b32_e64 v21, v21, v252, s[98:99]
	v_cndmask_b32_e64 v251, v226, v251, s[98:99]
	v_lshl_add_u64 v[226:227], v[34:35], 0, s[100:101]
	flat_store_dwordx4 v[34:35], v[248:251] nt
	flat_store_dwordx4 v[226:227], v[18:21] nt
	s_mov_b64 s[12:13], 0x160000
	v_pk_mul_f32 v[16:17], v[16:17], v[140:141] op_sel_hi:[1,0]
	v_mov_b32_e32 v21, 0
	v_mov_b32_e32 v34, 0
	v_mov_b32_e32 v35, 0
	v_max_f32_e32 v14, 0, v14
	v_mul_f32_e32 v20, v10, v10
	v_max_f32_e32 v10, 0, v15
	v_max_f32_e32 v11, 0, v11
	v_max_f32_e32 v12, 0, v12
	v_lshl_add_u64 v[18:19], v[142:143], 0, s[12:13]
	v_mul_f32_e32 v14, v14, v14
	v_mul_f32_e32 v10, v10, v10
	v_mul_f32_e32 v15, v11, v11
	v_max_f32_e32 v11, 0, v16
	v_mul_f32_e32 v16, v12, v12
	v_max_f32_e32 v12, 0, v17
	v_mov_b32_e32 v17, 0
	s_mov_b32 s12, 0x160000
	v_mul_f32_e32 v11, v11, v11
	v_max_f32_e32 v13, 0, v13
	v_mul_f32_e32 v12, v12, v12
	v_cvt_pk_bf16_f32 v10, v14, v10
	v_add_co_u32_e32 v14, vcc, s12, v142
	v_pk_mul_f32 v[4:5], v[4:5], v[140:141] op_sel_hi:[1,0]
	v_pk_mul_f32 v[2:3], v[2:3], v[140:141] op_sel_hi:[1,0]
	v_mul_f32_e32 v13, v13, v13
	v_cvt_pk_bf16_f32 v11, v11, v12
	v_cvt_pk_bf16_f32 v12, v20, v15
	v_mov_b32_e32 v20, 0
	v_addc_co_u32_e32 v15, vcc, 0, v143, vcc
	v_pk_mul_f32 v[8:9], v[8:9], v[140:141] op_sel_hi:[1,0]
	v_pk_mul_f32 v[6:7], v[6:7], v[140:141] op_sel_hi:[1,0]
	v_max_f32_e32 v2, 0, v2
	v_max_f32_e32 v3, 0, v3
	v_max_f32_e32 v4, 0, v4
	v_cvt_pk_bf16_f32 v13, v16, v13
	v_mov_b32_e32 v16, 0
	v_mov_b32_e32 v248, v10
	v_mov_b32_e32 v249, v11
	v_mov_b32_e32 v250, v12
	v_mov_b32_e32 v251, v13
	v_max_f32_e32 v5, 0, v5
	v_max_f32_e32 v6, 0, v6
	v_mov_b32_e32 v11, 0
	v_mov_b32_e32 v12, 0
	v_mov_b32_e32 v13, 0
	v_mov_b32_e32 v14, 0
	v_mov_b32_e32 v15, 0
	v_mul_f32_e32 v10, v2, v2
	v_max_f32_e32 v2, 0, v7
	v_mul_f32_e32 v7, v3, v3
	v_max_f32_e32 v3, 0, v8
	v_mul_f32_e32 v8, v4, v4
	v_max_f32_e32 v4, 0, v9
	v_mov_b32_e32 v9, 0
	v_mul_f32_e32 v2, v2, v2
	v_mul_f32_e32 v3, v3, v3
	v_mul_f32_e32 v4, v4, v4
	v_mul_f32_e32 v5, v5, v5
	s_mov_b64 s[12:13], -1
	s_andn2_b64 vcc, exec, s[40:41]
	v_mul_f32_e32 v6, v6, v6
	v_cvt_pk_bf16_f32 v2, v6, v2
	v_mov_b32_e32 v6, 0
	v_cvt_pk_bf16_f32 v3, v3, v4
	v_cvt_pk_bf16_f32 v4, v10, v7
	v_mov_b32_e32 v7, 0
	v_mov_b32_e32 v10, 0
	v_cvt_pk_bf16_f32 v5, v8, v5
	v_mov_b32_e32 v8, 0
	v_mov_b32_dpp v252, v248 row_ror:8 row_mask:0xf bank_mask:0xf
	v_mov_b32_dpp v226, v2 row_ror:8 row_mask:0xf bank_mask:0xf
	v_cndmask_b32_e64 v2, v2, v252, s[98:99]
	v_cndmask_b32_e64 v248, v226, v248, s[98:99]
	v_mov_b32_dpp v252, v249 row_ror:8 row_mask:0xf bank_mask:0xf
	v_mov_b32_dpp v226, v3 row_ror:8 row_mask:0xf bank_mask:0xf
	v_cndmask_b32_e64 v3, v3, v252, s[98:99]
	v_cndmask_b32_e64 v249, v226, v249, s[98:99]
	v_mov_b32_dpp v252, v250 row_ror:8 row_mask:0xf bank_mask:0xf
	v_mov_b32_dpp v226, v4 row_ror:8 row_mask:0xf bank_mask:0xf
	v_cndmask_b32_e64 v4, v4, v252, s[98:99]
	v_cndmask_b32_e64 v250, v226, v250, s[98:99]
	v_mov_b32_dpp v252, v251 row_ror:8 row_mask:0xf bank_mask:0xf
	v_mov_b32_dpp v226, v5 row_ror:8 row_mask:0xf bank_mask:0xf
	v_cndmask_b32_e64 v5, v5, v252, s[98:99]
	v_cndmask_b32_e64 v251, v226, v251, s[98:99]
	v_lshl_add_u64 v[226:227], v[18:19], 0, s[100:101]
	flat_store_dwordx4 v[18:19], v[248:251] nt
	flat_store_dwordx4 v[226:227], v[2:5] nt
	s_cbranch_vccnz .LBB0_553
	s_andn2_b64 vcc, exec, s[18:19]
	s_cbranch_vccnz .LBB0_552
	s_barrier
	s_branch .LBB0_552
